# row phases: the eight 4 KB parameter vectors are fetched once per workgroup (one vector per wave) and shared through LDS instead of every wave loading all of them from L2
# speedup vs baseline: 1.0097x; 1.0084x over previous
.LBB0_49:
	s_add_i32 s0, s76, -2
	s_mul_hi_i32 s1, s0, 0x38e38e39
	s_lshr_b32 s4, s1, 31
	s_ashr_i32 s1, s1, 1
	s_add_i32 s6, s1, s4
	s_mul_i32 s1, s6, 9
	s_mov_b32 s4, s6
	s_sub_i32 s20, s0, s1
	v_writelane_b32 v254, s4, 34
	s_add_u32 s0, s84, 0xaeca000
	s_addc_u32 s1, s85, 0
	v_writelane_b32 v254, s5, 35
	v_writelane_b32 v254, s0, 36
	v_readfirstlane_b32 s28, v160
	s_nop 0
	v_writelane_b32 v254, s1, 37
	s_nop 0
	v_readlane_b32 s0, v254, 32
	v_readlane_b32 s1, v254, 33
	v_readlane_b32 s4, v254, 14
	s_lshl_b64 s[0:1], s[0:1], 2
	v_readlane_b32 s18, v254, 28
	v_readlane_b32 s5, v254, 15
	v_readlane_b32 s19, v254, 29
	s_add_u32 s4, s18, s0
	s_addc_u32 s5, s19, s1
	v_readlane_b32 s6, v254, 16
	v_readlane_b32 s7, v254, 17
	v_readlane_b32 s8, v254, 18
	v_readlane_b32 s9, v254, 19
	v_readlane_b32 s10, v254, 20
	v_readlane_b32 s11, v254, 21
	v_readlane_b32 s12, v254, 22
	v_readlane_b32 s13, v254, 23
	v_readlane_b32 s14, v254, 24
	v_readlane_b32 s15, v254, 25
	v_readlane_b32 s16, v254, 26
	v_readlane_b32 s17, v254, 27
	v_writelane_b32 v254, s4, 38
	s_cmp_lt_i32 s20, 4
	s_nop 0
	v_writelane_b32 v254, s5, 39
	v_writelane_b32 v254, s20, 40
	s_mov_b64 s[4:5], -1
	s_cbranch_scc1 .LBB0_214
	v_readlane_b32 s4, v254, 40
	s_cmp_lt_i32 s4, 6
	s_mov_b64 s[4:5], -1
	s_cbranch_scc1 .LBB0_168
	v_readlane_b32 s4, v254, 40
	s_cmp_lt_i32 s4, 7
	s_mov_b64 s[4:5], -1
	s_cbranch_scc1 .LBB0_150
	v_readlane_b32 s4, v254, 40
	s_cmp_lt_i32 s4, 8
	s_mov_b64 s[4:5], -1
	s_cbranch_scc1 .LBB0_101
	v_readlane_b32 s4, v254, 40
	s_cmp_eq_u32 s4, 8
	s_cbranch_scc0 .LBB0_100
	s_cmp_eq_u32 s76, 37
	s_cbranch_scc1 .Lrow2_last
	v_readfirstlane_b32 s0, v160
	v_readlane_b32 s1, v252, 7
	s_lshr_b32 s0, s0, 6
	s_mov_b32 s73, s0
	s_add_i32 s0, s0, s1
	v_readlane_b32 s62, v254, 34
	s_sub_u32 s64, s78, 0x110
	s_subb_u32 s65, s79, 0
	s_load_dwordx2 s[66:67], s[64:65], 0x40
	s_load_dwordx2 s[10:11], s[64:65], 0xf8
	s_lshl_b32 s63, s0, 11
	s_add_u32 s4, s84, 0x167ca000
	s_addc_u32 s5, s85, 0
	s_add_u32 s4, s4, s63
	s_addc_u32 s5, s5, 0
	s_add_u32 s6, s84, 0x112ca000
	s_addc_u32 s7, s85, 0
	s_add_u32 s6, s6, s63
	s_addc_u32 s7, s7, 0
	v_and_b32_e32 v0, 63, v160
	v_lshlrev_b32_e32 v1, 4, v0
	v_lshlrev_b32_e32 v0, 3, v0
	v_add_u32_e32 v2, 0x400000, v0
	v_add_u32_e32 v3, 0x800000, v0
	v_add_u32_e32 v4, 0xc00000, v0
	v_add_u32_e32 v5, 0x1000000, v0
	global_load_dwordx2 v[8:9], v5, s[6:7] offset:0 nt
	global_load_dwordx2 v[10:11], v5, s[6:7] offset:512 nt
	global_load_dwordx2 v[12:13], v5, s[6:7] offset:1024 nt
	global_load_dwordx2 v[14:15], v5, s[6:7] offset:1536 nt
	global_load_dwordx2 v[16:17], v5, s[4:5] offset:0 nt
	global_load_dwordx2 v[18:19], v5, s[4:5] offset:512 nt
	global_load_dwordx2 v[20:21], v5, s[4:5] offset:1024 nt
	global_load_dwordx2 v[22:23], v5, s[4:5] offset:1536 nt
	s_add_u32 s8, s84, 0xaeca000
	s_addc_u32 s9, s85, 0
	s_add_u32 s8, s8, s63
	s_addc_u32 s9, s9, 0
	s_lshr_b32 s69, s0, 10
	s_add_i32 s69, s69, 1
	s_mul_i32 s69, s69, 0x6000
	s_mul_i32 s68, s62, 0x12000
	s_add_i32 s70, s62, 1
	s_mul_i32 s71, s70, 0x12000
	s_lshl_b32 s70, s70, 14
	s_lshl_b32 s72, s62, 14
	s_add_i32 s72, s72, 0x3000
	s_add_u32 s16, s84, 0x6605000
	s_addc_u32 s17, s85, 0
	s_add_u32 s16, s16, s68
	s_addc_u32 s17, s17, 0
	s_add_u32 s20, s84, 0x6600000
	s_addc_u32 s21, s85, 0
	s_add_u32 s20, s20, s71
	s_addc_u32 s21, s21, 0
	s_add_u32 s18, s20, 0x1000
	s_addc_u32 s19, s21, 0
	s_add_u32 s22, s16, s69
	s_addc_u32 s23, s17, 0
	s_add_u32 s60, s20, s69
	s_addc_u32 s61, s21, 0
	s_add_u32 s26, s18, s69
	s_addc_u32 s27, s19, 0
	s_lshl_b32 s63, s63, 1
	s_waitcnt lgkmcnt(0)
	s_add_u32 s12, s66, s72
	s_addc_u32 s13, s67, 0
	s_add_u32 s14, s66, s70
	s_addc_u32 s15, s67, 0
	s_add_u32 s10, s10, s63
	s_addc_u32 s11, s11, 0
	s_mov_b64 s[74:75], s[12:13]
	s_cmp_eq_u32 s73, 1
	s_cselect_b32 s74, s14, s74
	s_cselect_b32 s75, s15, s75
	s_cmp_eq_u32 s73, 2
	s_cselect_b32 s74, s16, s74
	s_cselect_b32 s75, s17, s75
	s_cmp_eq_u32 s73, 3
	s_cselect_b32 s74, s18, s74
	s_cselect_b32 s75, s19, s75
	s_cmp_eq_u32 s73, 4
	s_cselect_b32 s74, s20, s74
	s_cselect_b32 s75, s21, s75
	s_cmp_eq_u32 s73, 5
	s_cselect_b32 s74, s22, s74
	s_cselect_b32 s75, s23, s75
	s_cmp_eq_u32 s73, 6
	s_cselect_b32 s74, s26, s74
	s_cselect_b32 s75, s27, s75
	s_cmp_eq_u32 s73, 7
	s_cselect_b32 s74, s60, s74
	s_cselect_b32 s75, s61, s75
	global_load_dwordx4 v[222:225], v1, s[74:75] offset:0
	global_load_dwordx4 v[226:229], v1, s[74:75] offset:1024
	global_load_dwordx4 v[230:233], v1, s[74:75] offset:2048
	global_load_dwordx4 v[234:237], v1, s[74:75] offset:3072
	s_lshl_b32 s74, s73, 12
	v_add_u32_e32 v6, s74, v1
	global_load_dwordx2 v[24:25], v0, s[6:7] offset:0 nt
	global_load_dwordx2 v[26:27], v0, s[6:7] offset:512 nt
	global_load_dwordx2 v[28:29], v0, s[6:7] offset:1024 nt
	global_load_dwordx2 v[30:31], v0, s[6:7] offset:1536 nt
	global_load_dwordx2 v[32:33], v0, s[4:5] offset:0 nt
	global_load_dwordx2 v[34:35], v0, s[4:5] offset:512 nt
	global_load_dwordx2 v[36:37], v0, s[4:5] offset:1024 nt
	global_load_dwordx2 v[38:39], v0, s[4:5] offset:1536 nt
	global_load_dwordx2 v[40:41], v2, s[6:7] offset:0 nt
	global_load_dwordx2 v[42:43], v2, s[6:7] offset:512 nt
	global_load_dwordx2 v[44:45], v2, s[6:7] offset:1024 nt
	global_load_dwordx2 v[46:47], v2, s[6:7] offset:1536 nt
	global_load_dwordx2 v[48:49], v2, s[4:5] offset:0 nt
	global_load_dwordx2 v[50:51], v2, s[4:5] offset:512 nt
	global_load_dwordx2 v[52:53], v2, s[4:5] offset:1024 nt
	global_load_dwordx2 v[54:55], v2, s[4:5] offset:1536 nt
	s_waitcnt vmcnt(16)
	ds_write_b128 v6, v[222:225] offset:0
	ds_write_b128 v6, v[226:229] offset:1024
	ds_write_b128 v6, v[230:233] offset:2048
	ds_write_b128 v6, v[234:237] offset:3072
	s_waitcnt lgkmcnt(0)
	s_barrier
	ds_read_b128 v[56:59], v1 offset:0
	ds_read_b128 v[60:63], v1 offset:1024
	ds_read_b128 v[64:67], v1 offset:2048
	ds_read_b128 v[68:71], v1 offset:3072
	ds_read_b128 v[72:75], v1 offset:4096
	ds_read_b128 v[76:79], v1 offset:5120
	ds_read_b128 v[80:83], v1 offset:6144
	ds_read_b128 v[84:87], v1 offset:7168
	ds_read_b128 v[88:91], v1 offset:8192
	ds_read_b128 v[92:95], v1 offset:9216
	ds_read_b128 v[96:99], v1 offset:10240
	ds_read_b128 v[100:103], v1 offset:11264
	ds_read_b128 v[104:107], v1 offset:12288
	ds_read_b128 v[108:111], v1 offset:13312
	ds_read_b128 v[112:115], v1 offset:14336
	ds_read_b128 v[116:119], v1 offset:15360
	ds_read_b128 v[134:137], v1 offset:16384
	ds_read_b128 v[138:141], v1 offset:17408
	ds_read_b128 v[142:145], v1 offset:18432
	ds_read_b128 v[146:149], v1 offset:19456
	ds_read_b128 v[190:193], v1 offset:20480
	ds_read_b128 v[194:197], v1 offset:21504
	ds_read_b128 v[198:201], v1 offset:22528
	ds_read_b128 v[202:205], v1 offset:23552
	ds_read_b128 v[206:209], v1 offset:24576
	ds_read_b128 v[210:213], v1 offset:25600
	ds_read_b128 v[214:217], v1 offset:26624
	ds_read_b128 v[218:221], v1 offset:27648
	ds_read_b128 v[222:225], v1 offset:28672
	ds_read_b128 v[226:229], v1 offset:29696
	ds_read_b128 v[230:233], v1 offset:30720
	ds_read_b128 v[234:237], v1 offset:31744
	v_lshlrev_b32_e32 v246, 16, v8
	v_and_b32_e32 v8, 0xffff0000, v8
	v_lshlrev_b32_e32 v247, 16, v9
	v_and_b32_e32 v9, 0xffff0000, v9
	v_lshlrev_b32_e32 v248, 16, v10
	v_and_b32_e32 v10, 0xffff0000, v10
	v_lshlrev_b32_e32 v249, 16, v11
	v_and_b32_e32 v11, 0xffff0000, v11
	v_lshlrev_b32_e32 v250, 16, v12
	v_and_b32_e32 v12, 0xffff0000, v12
	v_lshlrev_b32_e32 v251, 16, v13
	v_and_b32_e32 v13, 0xffff0000, v13
	v_lshlrev_b32_e32 v176, 16, v14
	v_and_b32_e32 v14, 0xffff0000, v14
	v_lshlrev_b32_e32 v177, 16, v15
	v_and_b32_e32 v15, 0xffff0000, v15
	v_mul_f32_e32 v178, v246, v246
	v_fmac_f32_e32 v178, v8, v8
	v_fmac_f32_e32 v178, v247, v247
	v_fmac_f32_e32 v178, v9, v9
	v_fmac_f32_e32 v178, v248, v248
	v_fmac_f32_e32 v178, v10, v10
	v_fmac_f32_e32 v178, v249, v249
	v_fmac_f32_e32 v178, v11, v11
	v_fmac_f32_e32 v178, v250, v250
	v_fmac_f32_e32 v178, v12, v12
	v_fmac_f32_e32 v178, v251, v251
	v_fmac_f32_e32 v178, v13, v13
	v_fmac_f32_e32 v178, v176, v176
	v_fmac_f32_e32 v178, v14, v14
	v_fmac_f32_e32 v178, v177, v177
	v_fmac_f32_e32 v178, v15, v15
	v_lshlrev_b32_e32 v238, 16, v16
	v_and_b32_e32 v16, 0xffff0000, v16
	v_add_f32_dpp v178, v178, v178 quad_perm:[1,0,3,2] row_mask:0xf bank_mask:0xf bound_ctrl:1
	v_lshlrev_b32_e32 v239, 16, v17
	v_and_b32_e32 v17, 0xffff0000, v17
	v_add_f32_dpp v178, v178, v178 quad_perm:[2,3,0,1] row_mask:0xf bank_mask:0xf bound_ctrl:1
	v_lshlrev_b32_e32 v240, 16, v18
	v_and_b32_e32 v18, 0xffff0000, v18
	v_add_f32_dpp v178, v178, v178 row_half_mirror row_mask:0xf bank_mask:0xf bound_ctrl:1
	v_lshlrev_b32_e32 v241, 16, v19
	v_and_b32_e32 v19, 0xffff0000, v19
	v_add_f32_dpp v178, v178, v178 row_mirror row_mask:0xf bank_mask:0xf bound_ctrl:1
	v_lshlrev_b32_e32 v242, 16, v20
	v_and_b32_e32 v20, 0xffff0000, v20
	v_add_f32_dpp v178, v178, v178 row_bcast:15 row_mask:0xa bank_mask:0xf
	v_lshlrev_b32_e32 v243, 16, v21
	v_and_b32_e32 v21, 0xffff0000, v21
	v_add_f32_dpp v178, v178, v178 row_bcast:31 row_mask:0xc bank_mask:0xf
	v_lshlrev_b32_e32 v244, 16, v22
	v_and_b32_e32 v22, 0xffff0000, v22
	v_lshlrev_b32_e32 v245, 16, v23
	v_and_b32_e32 v23, 0xffff0000, v23
	v_readlane_b32 s0, v178, 63
	s_nop 1
	v_mov_b32_e32 v181, s0
	v_fmamk_f32 v181, v181, 0x3a800000, v161
	v_rsq_f32_e32 v179, v181
	s_nop 0
	s_waitcnt lgkmcnt(0)
	v_mul_f32_e32 v246, v246, v179
	v_mul_f32_e32 v8, v8, v179
	v_mul_f32_e32 v247, v247, v179
	v_mul_f32_e32 v9, v9, v179
	v_mul_f32_e32 v248, v248, v179
	v_mul_f32_e32 v10, v10, v179
	v_mul_f32_e32 v249, v249, v179
	v_mul_f32_e32 v11, v11, v179
	v_mul_f32_e32 v250, v250, v179
	v_mul_f32_e32 v12, v12, v179
	v_mul_f32_e32 v251, v251, v179
	v_mul_f32_e32 v13, v13, v179
	v_mul_f32_e32 v176, v176, v179
	v_mul_f32_e32 v14, v14, v179
	v_mul_f32_e32 v177, v177, v179
	v_mul_f32_e32 v15, v15, v179
	v_mul_f32_e32 v246, v246, v56
	v_mul_f32_e32 v8, v8, v57
	v_mul_f32_e32 v247, v247, v58
	v_mul_f32_e32 v9, v9, v59
	v_mul_f32_e32 v248, v248, v60
	v_mul_f32_e32 v10, v10, v61
	v_mul_f32_e32 v249, v249, v62
	v_mul_f32_e32 v11, v11, v63
	v_mul_f32_e32 v250, v250, v64
	v_mul_f32_e32 v12, v12, v65
	v_mul_f32_e32 v251, v251, v66
	v_mul_f32_e32 v13, v13, v67
	v_mul_f32_e32 v176, v176, v68
	v_mul_f32_e32 v14, v14, v69
	v_mul_f32_e32 v177, v177, v70
	v_mul_f32_e32 v15, v15, v71
	v_fmac_f32_e32 v238, v190, v246
	v_fmac_f32_e32 v16, v191, v8
	v_fmac_f32_e32 v239, v192, v247
	v_fmac_f32_e32 v17, v193, v9
	v_fmac_f32_e32 v240, v194, v248
	v_fmac_f32_e32 v18, v195, v10
	v_fmac_f32_e32 v241, v196, v249
	v_fmac_f32_e32 v19, v197, v11
	v_fmac_f32_e32 v242, v198, v250
	v_fmac_f32_e32 v20, v199, v12
	v_fmac_f32_e32 v243, v200, v251
	v_fmac_f32_e32 v21, v201, v13
	v_fmac_f32_e32 v244, v202, v176
	v_fmac_f32_e32 v22, v203, v14
	v_fmac_f32_e32 v245, v204, v177
	v_fmac_f32_e32 v23, v205, v15
	v_cvt_pk_bf16_f32 v120, v238, v16
	v_cvt_pk_bf16_f32 v121, v239, v17
	global_store_dwordx2 v5, v[120:121], s[4:5] offset:0 nt
	v_cvt_pk_bf16_f32 v122, v240, v18
	v_cvt_pk_bf16_f32 v123, v241, v19
	global_store_dwordx2 v5, v[122:123], s[4:5] offset:512 nt
	v_cvt_pk_bf16_f32 v124, v242, v20
	v_cvt_pk_bf16_f32 v125, v243, v21
	global_store_dwordx2 v5, v[124:125], s[4:5] offset:1024 nt
	v_cvt_pk_bf16_f32 v126, v244, v22
	v_cvt_pk_bf16_f32 v127, v245, v23
	global_store_dwordx2 v5, v[126:127], s[4:5] offset:1536 nt
	v_mul_f32_e32 v178, v238, v238
	v_fmac_f32_e32 v178, v16, v16
	v_fmac_f32_e32 v178, v239, v239
	v_fmac_f32_e32 v178, v17, v17
	v_fmac_f32_e32 v178, v240, v240
	v_fmac_f32_e32 v178, v18, v18
	v_fmac_f32_e32 v178, v241, v241
	v_fmac_f32_e32 v178, v19, v19
	v_fmac_f32_e32 v178, v242, v242
	v_fmac_f32_e32 v178, v20, v20
	v_fmac_f32_e32 v178, v243, v243
	v_fmac_f32_e32 v178, v21, v21
	v_fmac_f32_e32 v178, v244, v244
	v_fmac_f32_e32 v178, v22, v22
	v_fmac_f32_e32 v178, v245, v245
	v_fmac_f32_e32 v178, v23, v23
	v_add_f32_e32 v206, 1.0, v206
	v_add_f32_e32 v207, 1.0, v207
	v_add_f32_dpp v178, v178, v178 quad_perm:[1,0,3,2] row_mask:0xf bank_mask:0xf bound_ctrl:1
	v_add_f32_e32 v208, 1.0, v208
	v_add_f32_e32 v209, 1.0, v209
	v_add_f32_dpp v178, v178, v178 quad_perm:[2,3,0,1] row_mask:0xf bank_mask:0xf bound_ctrl:1
	v_add_f32_e32 v210, 1.0, v210
	v_add_f32_e32 v211, 1.0, v211
	v_add_f32_dpp v178, v178, v178 row_half_mirror row_mask:0xf bank_mask:0xf bound_ctrl:1
	v_add_f32_e32 v212, 1.0, v212
	v_add_f32_e32 v213, 1.0, v213
	v_add_f32_dpp v178, v178, v178 row_mirror row_mask:0xf bank_mask:0xf bound_ctrl:1
	v_add_f32_e32 v214, 1.0, v214
	v_add_f32_e32 v215, 1.0, v215
	v_add_f32_dpp v178, v178, v178 row_bcast:15 row_mask:0xa bank_mask:0xf
	v_add_f32_e32 v216, 1.0, v216
	v_add_f32_e32 v217, 1.0, v217
	v_add_f32_dpp v178, v178, v178 row_bcast:31 row_mask:0xc bank_mask:0xf
	v_add_f32_e32 v218, 1.0, v218
	v_add_f32_e32 v219, 1.0, v219
	v_add_f32_e32 v220, 1.0, v220
	v_add_f32_e32 v221, 1.0, v221
	v_readlane_b32 s0, v178, 63
	s_nop 1
	v_mov_b32_e32 v181, s0
	v_fmamk_f32 v181, v181, 0x3a800000, v161
	v_rsq_f32_e32 v180, v181
	s_nop 0
	v_mul_f32_e32 v238, v238, v180
	v_mul_f32_e32 v16, v16, v180
	v_mul_f32_e32 v239, v239, v180
	v_mul_f32_e32 v17, v17, v180
	v_mul_f32_e32 v240, v240, v180
	v_mul_f32_e32 v18, v18, v180
	v_mul_f32_e32 v241, v241, v180
	v_mul_f32_e32 v19, v19, v180
	v_mul_f32_e32 v242, v242, v180
	v_mul_f32_e32 v20, v20, v180
	v_mul_f32_e32 v243, v243, v180
	v_mul_f32_e32 v21, v21, v180
	v_mul_f32_e32 v244, v244, v180
	v_mul_f32_e32 v22, v22, v180
	v_mul_f32_e32 v245, v245, v180
	v_mul_f32_e32 v23, v23, v180
	v_mul_f32_e32 v238, v238, v72
	v_mul_f32_e32 v16, v16, v73
	v_mul_f32_e32 v239, v239, v74
	v_mul_f32_e32 v17, v17, v75
	v_mul_f32_e32 v240, v240, v76
	v_mul_f32_e32 v18, v18, v77
	v_mul_f32_e32 v241, v241, v78
	v_mul_f32_e32 v19, v19, v79
	v_mul_f32_e32 v242, v242, v80
	v_mul_f32_e32 v20, v20, v81
	v_mul_f32_e32 v243, v243, v82
	v_mul_f32_e32 v21, v21, v83
	v_mul_f32_e32 v244, v244, v84
	v_mul_f32_e32 v22, v22, v85
	v_mul_f32_e32 v245, v245, v86
	v_mul_f32_e32 v23, v23, v87
	v_fma_f32 v238, v238, v206, v222
	v_fma_f32 v16, v16, v207, v223
	v_fma_f32 v239, v239, v208, v224
	v_fma_f32 v17, v17, v209, v225
	v_fma_f32 v240, v240, v210, v226
	v_fma_f32 v18, v18, v211, v227
	v_fma_f32 v241, v241, v212, v228
	v_fma_f32 v19, v19, v213, v229
	v_fma_f32 v242, v242, v214, v230
	v_fma_f32 v20, v20, v215, v231
	v_fma_f32 v243, v243, v216, v232
	v_fma_f32 v21, v21, v217, v233
	v_fma_f32 v244, v244, v218, v234
	v_fma_f32 v22, v22, v219, v235
	v_fma_f32 v245, v245, v220, v236
	v_fma_f32 v23, v23, v221, v237
	v_cvt_pk_bf16_f32 v150, v238, v16
	v_cvt_pk_bf16_f32 v151, v239, v17
	global_store_dwordx2 v5, v[150:151], s[8:9] offset:0
	v_cvt_pk_bf16_f32 v152, v240, v18
	v_cvt_pk_bf16_f32 v153, v241, v19
	global_store_dwordx2 v5, v[152:153], s[8:9] offset:512
	v_cvt_pk_bf16_f32 v154, v242, v20
	v_cvt_pk_bf16_f32 v155, v243, v21
	global_store_dwordx2 v5, v[154:155], s[8:9] offset:1024
	v_cvt_pk_bf16_f32 v156, v244, v22
	v_cvt_pk_bf16_f32 v157, v245, v23
	global_store_dwordx2 v5, v[156:157], s[8:9] offset:1536
	global_load_dwordx2 v[8:9], v3, s[6:7] offset:0 nt
	global_load_dwordx2 v[10:11], v3, s[6:7] offset:512 nt
	global_load_dwordx2 v[12:13], v3, s[6:7] offset:1024 nt
	global_load_dwordx2 v[14:15], v3, s[6:7] offset:1536 nt
	global_load_dwordx2 v[16:17], v3, s[4:5] offset:0 nt
	global_load_dwordx2 v[18:19], v3, s[4:5] offset:512 nt
	global_load_dwordx2 v[20:21], v3, s[4:5] offset:1024 nt
	global_load_dwordx2 v[22:23], v3, s[4:5] offset:1536 nt
	global_load_dwordx2 v[190:191], v4, s[6:7] offset:0 nt
	global_load_dwordx2 v[192:193], v4, s[6:7] offset:512 nt
	global_load_dwordx2 v[194:195], v4, s[6:7] offset:1024 nt
	global_load_dwordx2 v[196:197], v4, s[6:7] offset:1536 nt
	global_load_dwordx2 v[198:199], v4, s[4:5] offset:0 nt
	global_load_dwordx2 v[200:201], v4, s[4:5] offset:512 nt
	global_load_dwordx2 v[202:203], v4, s[4:5] offset:1024 nt
	global_load_dwordx2 v[204:205], v4, s[4:5] offset:1536 nt
	s_waitcnt vmcnt(36)
	v_lshlrev_b32_e32 v246, 16, v24
	v_and_b32_e32 v24, 0xffff0000, v24
	v_lshlrev_b32_e32 v247, 16, v25
	v_and_b32_e32 v25, 0xffff0000, v25
	v_lshlrev_b32_e32 v248, 16, v26
	v_and_b32_e32 v26, 0xffff0000, v26
	v_lshlrev_b32_e32 v249, 16, v27
	v_and_b32_e32 v27, 0xffff0000, v27
	v_lshlrev_b32_e32 v250, 16, v28
	v_and_b32_e32 v28, 0xffff0000, v28
	v_lshlrev_b32_e32 v251, 16, v29
	v_and_b32_e32 v29, 0xffff0000, v29
	v_lshlrev_b32_e32 v176, 16, v30
	v_and_b32_e32 v30, 0xffff0000, v30
	v_lshlrev_b32_e32 v177, 16, v31
	v_and_b32_e32 v31, 0xffff0000, v31
	v_mul_f32_e32 v178, v246, v246
	v_fmac_f32_e32 v178, v24, v24
	v_fmac_f32_e32 v178, v247, v247
	v_fmac_f32_e32 v178, v25, v25
	v_fmac_f32_e32 v178, v248, v248
	v_fmac_f32_e32 v178, v26, v26
	v_fmac_f32_e32 v178, v249, v249
	v_fmac_f32_e32 v178, v27, v27
	v_fmac_f32_e32 v178, v250, v250
	v_fmac_f32_e32 v178, v28, v28
	v_fmac_f32_e32 v178, v251, v251
	v_fmac_f32_e32 v178, v29, v29
	v_fmac_f32_e32 v178, v176, v176
	v_fmac_f32_e32 v178, v30, v30
	v_fmac_f32_e32 v178, v177, v177
	v_fmac_f32_e32 v178, v31, v31
	s_waitcnt vmcnt(32)
	v_lshlrev_b32_e32 v238, 16, v32
	v_and_b32_e32 v32, 0xffff0000, v32
	v_add_f32_dpp v178, v178, v178 quad_perm:[1,0,3,2] row_mask:0xf bank_mask:0xf bound_ctrl:1
	v_lshlrev_b32_e32 v239, 16, v33
	v_and_b32_e32 v33, 0xffff0000, v33
	v_add_f32_dpp v178, v178, v178 quad_perm:[2,3,0,1] row_mask:0xf bank_mask:0xf bound_ctrl:1
	v_lshlrev_b32_e32 v240, 16, v34
	v_and_b32_e32 v34, 0xffff0000, v34
	v_add_f32_dpp v178, v178, v178 row_half_mirror row_mask:0xf bank_mask:0xf bound_ctrl:1
	v_lshlrev_b32_e32 v241, 16, v35
	v_and_b32_e32 v35, 0xffff0000, v35
	v_add_f32_dpp v178, v178, v178 row_mirror row_mask:0xf bank_mask:0xf bound_ctrl:1
	v_lshlrev_b32_e32 v242, 16, v36
	v_and_b32_e32 v36, 0xffff0000, v36
	v_add_f32_dpp v178, v178, v178 row_bcast:15 row_mask:0xa bank_mask:0xf
	v_lshlrev_b32_e32 v243, 16, v37
	v_and_b32_e32 v37, 0xffff0000, v37
	v_add_f32_dpp v178, v178, v178 row_bcast:31 row_mask:0xc bank_mask:0xf
	v_lshlrev_b32_e32 v244, 16, v38
	v_and_b32_e32 v38, 0xffff0000, v38
	v_lshlrev_b32_e32 v245, 16, v39
	v_and_b32_e32 v39, 0xffff0000, v39
	v_readlane_b32 s0, v178, 63
	s_nop 1
	v_mov_b32_e32 v181, s0
	v_fmamk_f32 v181, v181, 0x3a800000, v161
	v_rsq_f32_e32 v179, v181
	s_nop 0
	v_mul_f32_e32 v246, v246, v179
	v_mul_f32_e32 v24, v24, v179
	v_mul_f32_e32 v247, v247, v179
	v_mul_f32_e32 v25, v25, v179
	v_mul_f32_e32 v248, v248, v179
	v_mul_f32_e32 v26, v26, v179
	v_mul_f32_e32 v249, v249, v179
	v_mul_f32_e32 v27, v27, v179
	v_mul_f32_e32 v250, v250, v179
	v_mul_f32_e32 v28, v28, v179
	v_mul_f32_e32 v251, v251, v179
	v_mul_f32_e32 v29, v29, v179
	v_mul_f32_e32 v176, v176, v179
	v_mul_f32_e32 v30, v30, v179
	v_mul_f32_e32 v177, v177, v179
	v_mul_f32_e32 v31, v31, v179
	v_mul_f32_e32 v246, v246, v56
	v_mul_f32_e32 v24, v24, v57
	v_mul_f32_e32 v247, v247, v58
	v_mul_f32_e32 v25, v25, v59
	v_mul_f32_e32 v248, v248, v60
	v_mul_f32_e32 v26, v26, v61
	v_mul_f32_e32 v249, v249, v62
	v_mul_f32_e32 v27, v27, v63
	v_mul_f32_e32 v250, v250, v64
	v_mul_f32_e32 v28, v28, v65
	v_mul_f32_e32 v251, v251, v66
	v_mul_f32_e32 v29, v29, v67
	v_mul_f32_e32 v176, v176, v68
	v_mul_f32_e32 v30, v30, v69
	v_mul_f32_e32 v177, v177, v70
	v_mul_f32_e32 v31, v31, v71
	v_fmac_f32_e32 v238, v88, v246
	v_fmac_f32_e32 v32, v89, v24
	v_fmac_f32_e32 v239, v90, v247
	v_fmac_f32_e32 v33, v91, v25
	v_fmac_f32_e32 v240, v92, v248
	v_fmac_f32_e32 v34, v93, v26
	v_fmac_f32_e32 v241, v94, v249
	v_fmac_f32_e32 v35, v95, v27
	v_fmac_f32_e32 v242, v96, v250
	v_fmac_f32_e32 v36, v97, v28
	v_fmac_f32_e32 v243, v98, v251
	v_fmac_f32_e32 v37, v99, v29
	v_fmac_f32_e32 v244, v100, v176
	v_fmac_f32_e32 v38, v101, v30
	v_fmac_f32_e32 v245, v102, v177
	v_fmac_f32_e32 v39, v103, v31
	v_cvt_pk_bf16_f32 v120, v238, v32
	v_cvt_pk_bf16_f32 v121, v239, v33
	global_store_dwordx2 v0, v[120:121], s[4:5] offset:0 nt
	v_cvt_pk_bf16_f32 v122, v240, v34
	v_cvt_pk_bf16_f32 v123, v241, v35
	global_store_dwordx2 v0, v[122:123], s[4:5] offset:512 nt
	v_cvt_pk_bf16_f32 v124, v242, v36
	v_cvt_pk_bf16_f32 v125, v243, v37
	global_store_dwordx2 v0, v[124:125], s[4:5] offset:1024 nt
	v_cvt_pk_bf16_f32 v126, v244, v38
	v_cvt_pk_bf16_f32 v127, v245, v39
	global_store_dwordx2 v0, v[126:127], s[4:5] offset:1536 nt
	v_mul_f32_e32 v178, v238, v238
	v_fmac_f32_e32 v178, v32, v32
	v_fmac_f32_e32 v178, v239, v239
	v_fmac_f32_e32 v178, v33, v33
	v_fmac_f32_e32 v178, v240, v240
	v_fmac_f32_e32 v178, v34, v34
	v_fmac_f32_e32 v178, v241, v241
	v_fmac_f32_e32 v178, v35, v35
	v_fmac_f32_e32 v178, v242, v242
	v_fmac_f32_e32 v178, v36, v36
	v_fmac_f32_e32 v178, v243, v243
	v_fmac_f32_e32 v178, v37, v37
	v_fmac_f32_e32 v178, v244, v244
	v_fmac_f32_e32 v178, v38, v38
	v_fmac_f32_e32 v178, v245, v245
	v_fmac_f32_e32 v178, v39, v39
	v_add_f32_e32 v104, 1.0, v104
	v_add_f32_e32 v105, 1.0, v105
	v_add_f32_dpp v178, v178, v178 quad_perm:[1,0,3,2] row_mask:0xf bank_mask:0xf bound_ctrl:1
	v_add_f32_e32 v106, 1.0, v106
	v_add_f32_e32 v107, 1.0, v107
	v_add_f32_dpp v178, v178, v178 quad_perm:[2,3,0,1] row_mask:0xf bank_mask:0xf bound_ctrl:1
	v_add_f32_e32 v108, 1.0, v108
	v_add_f32_e32 v109, 1.0, v109
	v_add_f32_dpp v178, v178, v178 row_half_mirror row_mask:0xf bank_mask:0xf bound_ctrl:1
	v_add_f32_e32 v110, 1.0, v110
	v_add_f32_e32 v111, 1.0, v111
	v_add_f32_dpp v178, v178, v178 row_mirror row_mask:0xf bank_mask:0xf bound_ctrl:1
	v_add_f32_e32 v112, 1.0, v112
	v_add_f32_e32 v113, 1.0, v113
	v_add_f32_dpp v178, v178, v178 row_bcast:15 row_mask:0xa bank_mask:0xf
	v_add_f32_e32 v114, 1.0, v114
	v_add_f32_e32 v115, 1.0, v115
	v_add_f32_dpp v178, v178, v178 row_bcast:31 row_mask:0xc bank_mask:0xf
	v_add_f32_e32 v116, 1.0, v116
	v_add_f32_e32 v117, 1.0, v117
	v_add_f32_e32 v118, 1.0, v118
	v_add_f32_e32 v119, 1.0, v119
	v_readlane_b32 s0, v178, 63
	s_nop 1
	v_mov_b32_e32 v181, s0
	v_fmamk_f32 v181, v181, 0x3a800000, v161
	v_rsq_f32_e32 v180, v181
	s_nop 0
	v_mul_f32_e32 v238, v238, v180
	v_mul_f32_e32 v32, v32, v180
	v_mul_f32_e32 v239, v239, v180
	v_mul_f32_e32 v33, v33, v180
	v_mul_f32_e32 v240, v240, v180
	v_mul_f32_e32 v34, v34, v180
	v_mul_f32_e32 v241, v241, v180
	v_mul_f32_e32 v35, v35, v180
	v_mul_f32_e32 v242, v242, v180
	v_mul_f32_e32 v36, v36, v180
	v_mul_f32_e32 v243, v243, v180
	v_mul_f32_e32 v37, v37, v180
	v_mul_f32_e32 v244, v244, v180
	v_mul_f32_e32 v38, v38, v180
	v_mul_f32_e32 v245, v245, v180
	v_mul_f32_e32 v39, v39, v180
	v_mul_f32_e32 v238, v238, v72
	v_mul_f32_e32 v32, v32, v73
	v_mul_f32_e32 v239, v239, v74
	v_mul_f32_e32 v33, v33, v75
	v_mul_f32_e32 v240, v240, v76
	v_mul_f32_e32 v34, v34, v77
	v_mul_f32_e32 v241, v241, v78
	v_mul_f32_e32 v35, v35, v79
	v_mul_f32_e32 v242, v242, v80
	v_mul_f32_e32 v36, v36, v81
	v_mul_f32_e32 v243, v243, v82
	v_mul_f32_e32 v37, v37, v83
	v_mul_f32_e32 v244, v244, v84
	v_mul_f32_e32 v38, v38, v85
	v_mul_f32_e32 v245, v245, v86
	v_mul_f32_e32 v39, v39, v87
	v_fma_f32 v238, v238, v104, v134
	v_fma_f32 v32, v32, v105, v135
	v_fma_f32 v239, v239, v106, v136
	v_fma_f32 v33, v33, v107, v137
	v_fma_f32 v240, v240, v108, v138
	v_fma_f32 v34, v34, v109, v139
	v_fma_f32 v241, v241, v110, v140
	v_fma_f32 v35, v35, v111, v141
	v_fma_f32 v242, v242, v112, v142
	v_fma_f32 v36, v36, v113, v143
	v_fma_f32 v243, v243, v114, v144
	v_fma_f32 v37, v37, v115, v145
	v_fma_f32 v244, v244, v116, v146
	v_fma_f32 v38, v38, v117, v147
	v_fma_f32 v245, v245, v118, v148
	v_fma_f32 v39, v39, v119, v149
	v_cvt_pk_bf16_f32 v150, v238, v32
	v_cvt_pk_bf16_f32 v151, v239, v33
	global_store_dwordx2 v0, v[150:151], s[8:9] offset:0
	v_cvt_pk_bf16_f32 v152, v240, v34
	v_cvt_pk_bf16_f32 v153, v241, v35
	global_store_dwordx2 v0, v[152:153], s[8:9] offset:512
	v_cvt_pk_bf16_f32 v154, v242, v36
	v_cvt_pk_bf16_f32 v155, v243, v37
	global_store_dwordx2 v0, v[154:155], s[8:9] offset:1024
	v_cvt_pk_bf16_f32 v156, v244, v38
	v_cvt_pk_bf16_f32 v157, v245, v39
	global_store_dwordx2 v0, v[156:157], s[8:9] offset:1536
	s_waitcnt vmcnt(36)
	v_lshlrev_b32_e32 v246, 16, v40
	v_and_b32_e32 v40, 0xffff0000, v40
	v_lshlrev_b32_e32 v247, 16, v41
	v_and_b32_e32 v41, 0xffff0000, v41
	v_lshlrev_b32_e32 v248, 16, v42
	v_and_b32_e32 v42, 0xffff0000, v42
	v_lshlrev_b32_e32 v249, 16, v43
	v_and_b32_e32 v43, 0xffff0000, v43
	v_lshlrev_b32_e32 v250, 16, v44
	v_and_b32_e32 v44, 0xffff0000, v44
	v_lshlrev_b32_e32 v251, 16, v45
	v_and_b32_e32 v45, 0xffff0000, v45
	v_lshlrev_b32_e32 v176, 16, v46
	v_and_b32_e32 v46, 0xffff0000, v46
	v_lshlrev_b32_e32 v177, 16, v47
	v_and_b32_e32 v47, 0xffff0000, v47
	v_mul_f32_e32 v178, v246, v246
	v_fmac_f32_e32 v178, v40, v40
	v_fmac_f32_e32 v178, v247, v247
	v_fmac_f32_e32 v178, v41, v41
	v_fmac_f32_e32 v178, v248, v248
	v_fmac_f32_e32 v178, v42, v42
	v_fmac_f32_e32 v178, v249, v249
	v_fmac_f32_e32 v178, v43, v43
	v_fmac_f32_e32 v178, v250, v250
	v_fmac_f32_e32 v178, v44, v44
	v_fmac_f32_e32 v178, v251, v251
	v_fmac_f32_e32 v178, v45, v45
	v_fmac_f32_e32 v178, v176, v176
	v_fmac_f32_e32 v178, v46, v46
	v_fmac_f32_e32 v178, v177, v177
	v_fmac_f32_e32 v178, v47, v47
	s_waitcnt vmcnt(32)
	v_lshlrev_b32_e32 v238, 16, v48
	v_and_b32_e32 v48, 0xffff0000, v48
	v_add_f32_dpp v178, v178, v178 quad_perm:[1,0,3,2] row_mask:0xf bank_mask:0xf bound_ctrl:1
	v_lshlrev_b32_e32 v239, 16, v49
	v_and_b32_e32 v49, 0xffff0000, v49
	v_add_f32_dpp v178, v178, v178 quad_perm:[2,3,0,1] row_mask:0xf bank_mask:0xf bound_ctrl:1
	v_lshlrev_b32_e32 v240, 16, v50
	v_and_b32_e32 v50, 0xffff0000, v50
	v_add_f32_dpp v178, v178, v178 row_half_mirror row_mask:0xf bank_mask:0xf bound_ctrl:1
	v_lshlrev_b32_e32 v241, 16, v51
	v_and_b32_e32 v51, 0xffff0000, v51
	v_add_f32_dpp v178, v178, v178 row_mirror row_mask:0xf bank_mask:0xf bound_ctrl:1
	v_lshlrev_b32_e32 v242, 16, v52
	v_and_b32_e32 v52, 0xffff0000, v52
	v_add_f32_dpp v178, v178, v178 row_bcast:15 row_mask:0xa bank_mask:0xf
	v_lshlrev_b32_e32 v243, 16, v53
	v_and_b32_e32 v53, 0xffff0000, v53
	v_add_f32_dpp v178, v178, v178 row_bcast:31 row_mask:0xc bank_mask:0xf
	v_lshlrev_b32_e32 v244, 16, v54
	v_and_b32_e32 v54, 0xffff0000, v54
	v_lshlrev_b32_e32 v245, 16, v55
	v_and_b32_e32 v55, 0xffff0000, v55
	v_readlane_b32 s0, v178, 63
	s_nop 1
	v_mov_b32_e32 v181, s0
	v_fmamk_f32 v181, v181, 0x3a800000, v161
	v_rsq_f32_e32 v179, v181
	s_nop 0
	v_mul_f32_e32 v246, v246, v179
	v_mul_f32_e32 v40, v40, v179
	v_mul_f32_e32 v247, v247, v179
	v_mul_f32_e32 v41, v41, v179
	v_mul_f32_e32 v248, v248, v179
	v_mul_f32_e32 v42, v42, v179
	v_mul_f32_e32 v249, v249, v179
	v_mul_f32_e32 v43, v43, v179
	v_mul_f32_e32 v250, v250, v179
	v_mul_f32_e32 v44, v44, v179
	v_mul_f32_e32 v251, v251, v179
	v_mul_f32_e32 v45, v45, v179
	v_mul_f32_e32 v176, v176, v179
	v_mul_f32_e32 v46, v46, v179
	v_mul_f32_e32 v177, v177, v179
	v_mul_f32_e32 v47, v47, v179
	v_mul_f32_e32 v246, v246, v56
	v_mul_f32_e32 v40, v40, v57
	v_mul_f32_e32 v247, v247, v58
	v_mul_f32_e32 v41, v41, v59
	v_mul_f32_e32 v248, v248, v60
	v_mul_f32_e32 v42, v42, v61
	v_mul_f32_e32 v249, v249, v62
	v_mul_f32_e32 v43, v43, v63
	v_mul_f32_e32 v250, v250, v64
	v_mul_f32_e32 v44, v44, v65
	v_mul_f32_e32 v251, v251, v66
	v_mul_f32_e32 v45, v45, v67
	v_mul_f32_e32 v176, v176, v68
	v_mul_f32_e32 v46, v46, v69
	v_mul_f32_e32 v177, v177, v70
	v_mul_f32_e32 v47, v47, v71
	v_fmac_f32_e32 v238, v88, v246
	v_fmac_f32_e32 v48, v89, v40
	v_fmac_f32_e32 v239, v90, v247
	v_fmac_f32_e32 v49, v91, v41
	v_fmac_f32_e32 v240, v92, v248
	v_fmac_f32_e32 v50, v93, v42
	v_fmac_f32_e32 v241, v94, v249
	v_fmac_f32_e32 v51, v95, v43
	v_fmac_f32_e32 v242, v96, v250
	v_fmac_f32_e32 v52, v97, v44
	v_fmac_f32_e32 v243, v98, v251
	v_fmac_f32_e32 v53, v99, v45
	v_fmac_f32_e32 v244, v100, v176
	v_fmac_f32_e32 v54, v101, v46
	v_fmac_f32_e32 v245, v102, v177
	v_fmac_f32_e32 v55, v103, v47
	v_cvt_pk_bf16_f32 v120, v238, v48
	v_cvt_pk_bf16_f32 v121, v239, v49
	global_store_dwordx2 v2, v[120:121], s[4:5] offset:0 nt
	v_cvt_pk_bf16_f32 v122, v240, v50
	v_cvt_pk_bf16_f32 v123, v241, v51
	global_store_dwordx2 v2, v[122:123], s[4:5] offset:512 nt
	v_cvt_pk_bf16_f32 v124, v242, v52
	v_cvt_pk_bf16_f32 v125, v243, v53
	global_store_dwordx2 v2, v[124:125], s[4:5] offset:1024 nt
	v_cvt_pk_bf16_f32 v126, v244, v54
	v_cvt_pk_bf16_f32 v127, v245, v55
	global_store_dwordx2 v2, v[126:127], s[4:5] offset:1536 nt
	v_mul_f32_e32 v178, v238, v238
	v_fmac_f32_e32 v178, v48, v48
	v_fmac_f32_e32 v178, v239, v239
	v_fmac_f32_e32 v178, v49, v49
	v_fmac_f32_e32 v178, v240, v240
	v_fmac_f32_e32 v178, v50, v50
	v_fmac_f32_e32 v178, v241, v241
	v_fmac_f32_e32 v178, v51, v51
	v_fmac_f32_e32 v178, v242, v242
	v_fmac_f32_e32 v178, v52, v52
	v_fmac_f32_e32 v178, v243, v243
	v_fmac_f32_e32 v178, v53, v53
	v_fmac_f32_e32 v178, v244, v244
	v_fmac_f32_e32 v178, v54, v54
	v_fmac_f32_e32 v178, v245, v245
	v_fmac_f32_e32 v178, v55, v55
	s_nop 1
	v_add_f32_dpp v178, v178, v178 quad_perm:[1,0,3,2] row_mask:0xf bank_mask:0xf bound_ctrl:1
	s_nop 1
	v_add_f32_dpp v178, v178, v178 quad_perm:[2,3,0,1] row_mask:0xf bank_mask:0xf bound_ctrl:1
	s_nop 1
	v_add_f32_dpp v178, v178, v178 row_half_mirror row_mask:0xf bank_mask:0xf bound_ctrl:1
	s_nop 1
	v_add_f32_dpp v178, v178, v178 row_mirror row_mask:0xf bank_mask:0xf bound_ctrl:1
	s_nop 1
	v_add_f32_dpp v178, v178, v178 row_bcast:15 row_mask:0xa bank_mask:0xf
	s_nop 1
	v_add_f32_dpp v178, v178, v178 row_bcast:31 row_mask:0xc bank_mask:0xf
	s_nop 0
	v_readlane_b32 s0, v178, 63
	s_nop 1
	v_mov_b32_e32 v181, s0
	v_fmamk_f32 v181, v181, 0x3a800000, v161
	v_rsq_f32_e32 v180, v181
	s_nop 0
	v_mul_f32_e32 v238, v238, v180
	v_mul_f32_e32 v48, v48, v180
	v_mul_f32_e32 v239, v239, v180
	v_mul_f32_e32 v49, v49, v180
	v_mul_f32_e32 v240, v240, v180
	v_mul_f32_e32 v50, v50, v180
	v_mul_f32_e32 v241, v241, v180
	v_mul_f32_e32 v51, v51, v180
	v_mul_f32_e32 v242, v242, v180
	v_mul_f32_e32 v52, v52, v180
	v_mul_f32_e32 v243, v243, v180
	v_mul_f32_e32 v53, v53, v180
	v_mul_f32_e32 v244, v244, v180
	v_mul_f32_e32 v54, v54, v180
	v_mul_f32_e32 v245, v245, v180
	v_mul_f32_e32 v55, v55, v180
	v_mul_f32_e32 v238, v238, v72
	v_mul_f32_e32 v48, v48, v73
	v_mul_f32_e32 v239, v239, v74
	v_mul_f32_e32 v49, v49, v75
	v_mul_f32_e32 v240, v240, v76
	v_mul_f32_e32 v50, v50, v77
	v_mul_f32_e32 v241, v241, v78
	v_mul_f32_e32 v51, v51, v79
	v_mul_f32_e32 v242, v242, v80
	v_mul_f32_e32 v52, v52, v81
	v_mul_f32_e32 v243, v243, v82
	v_mul_f32_e32 v53, v53, v83
	v_mul_f32_e32 v244, v244, v84
	v_mul_f32_e32 v54, v54, v85
	v_mul_f32_e32 v245, v245, v86
	v_mul_f32_e32 v55, v55, v87
	v_fma_f32 v238, v238, v104, v134
	v_fma_f32 v48, v48, v105, v135
	v_fma_f32 v239, v239, v106, v136
	v_fma_f32 v49, v49, v107, v137
	v_fma_f32 v240, v240, v108, v138
	v_fma_f32 v50, v50, v109, v139
	v_fma_f32 v241, v241, v110, v140
	v_fma_f32 v51, v51, v111, v141
	v_fma_f32 v242, v242, v112, v142
	v_fma_f32 v52, v52, v113, v143
	v_fma_f32 v243, v243, v114, v144
	v_fma_f32 v53, v53, v115, v145
	v_fma_f32 v244, v244, v116, v146
	v_fma_f32 v54, v54, v117, v147
	v_fma_f32 v245, v245, v118, v148
	v_fma_f32 v55, v55, v119, v149
	v_cvt_pk_bf16_f32 v150, v238, v48
	v_cvt_pk_bf16_f32 v151, v239, v49
	global_store_dwordx2 v2, v[150:151], s[8:9] offset:0
	v_cvt_pk_bf16_f32 v152, v240, v50
	v_cvt_pk_bf16_f32 v153, v241, v51
	global_store_dwordx2 v2, v[152:153], s[8:9] offset:512
	v_cvt_pk_bf16_f32 v154, v242, v52
	v_cvt_pk_bf16_f32 v155, v243, v53
	global_store_dwordx2 v2, v[154:155], s[8:9] offset:1024
	v_cvt_pk_bf16_f32 v156, v244, v54
	v_cvt_pk_bf16_f32 v157, v245, v55
	global_store_dwordx2 v2, v[156:157], s[8:9] offset:1536
	s_waitcnt vmcnt(28)
	v_lshlrev_b32_e32 v246, 16, v8
	v_and_b32_e32 v8, 0xffff0000, v8
	v_lshlrev_b32_e32 v247, 16, v9
	v_and_b32_e32 v9, 0xffff0000, v9
	v_lshlrev_b32_e32 v248, 16, v10
	v_and_b32_e32 v10, 0xffff0000, v10
	v_lshlrev_b32_e32 v249, 16, v11
	v_and_b32_e32 v11, 0xffff0000, v11
	v_lshlrev_b32_e32 v250, 16, v12
	v_and_b32_e32 v12, 0xffff0000, v12
	v_lshlrev_b32_e32 v251, 16, v13
	v_and_b32_e32 v13, 0xffff0000, v13
	v_lshlrev_b32_e32 v176, 16, v14
	v_and_b32_e32 v14, 0xffff0000, v14
	v_lshlrev_b32_e32 v177, 16, v15
	v_and_b32_e32 v15, 0xffff0000, v15
	v_mul_f32_e32 v178, v246, v246
	v_fmac_f32_e32 v178, v8, v8
	v_fmac_f32_e32 v178, v247, v247
	v_fmac_f32_e32 v178, v9, v9
	v_fmac_f32_e32 v178, v248, v248
	v_fmac_f32_e32 v178, v10, v10
	v_fmac_f32_e32 v178, v249, v249
	v_fmac_f32_e32 v178, v11, v11
	v_fmac_f32_e32 v178, v250, v250
	v_fmac_f32_e32 v178, v12, v12
	v_fmac_f32_e32 v178, v251, v251
	v_fmac_f32_e32 v178, v13, v13
	v_fmac_f32_e32 v178, v176, v176
	v_fmac_f32_e32 v178, v14, v14
	v_fmac_f32_e32 v178, v177, v177
	v_fmac_f32_e32 v178, v15, v15
	s_waitcnt vmcnt(24)
	v_lshlrev_b32_e32 v238, 16, v16
	v_and_b32_e32 v16, 0xffff0000, v16
	v_add_f32_dpp v178, v178, v178 quad_perm:[1,0,3,2] row_mask:0xf bank_mask:0xf bound_ctrl:1
	v_lshlrev_b32_e32 v239, 16, v17
	v_and_b32_e32 v17, 0xffff0000, v17
	v_add_f32_dpp v178, v178, v178 quad_perm:[2,3,0,1] row_mask:0xf bank_mask:0xf bound_ctrl:1
	v_lshlrev_b32_e32 v240, 16, v18
	v_and_b32_e32 v18, 0xffff0000, v18
	v_add_f32_dpp v178, v178, v178 row_half_mirror row_mask:0xf bank_mask:0xf bound_ctrl:1
	v_lshlrev_b32_e32 v241, 16, v19
	v_and_b32_e32 v19, 0xffff0000, v19
	v_add_f32_dpp v178, v178, v178 row_mirror row_mask:0xf bank_mask:0xf bound_ctrl:1
	v_lshlrev_b32_e32 v242, 16, v20
	v_and_b32_e32 v20, 0xffff0000, v20
	v_add_f32_dpp v178, v178, v178 row_bcast:15 row_mask:0xa bank_mask:0xf
	v_lshlrev_b32_e32 v243, 16, v21
	v_and_b32_e32 v21, 0xffff0000, v21
	v_add_f32_dpp v178, v178, v178 row_bcast:31 row_mask:0xc bank_mask:0xf
	v_lshlrev_b32_e32 v244, 16, v22
	v_and_b32_e32 v22, 0xffff0000, v22
	v_lshlrev_b32_e32 v245, 16, v23
	v_and_b32_e32 v23, 0xffff0000, v23
	v_readlane_b32 s0, v178, 63
	s_nop 1
	v_mov_b32_e32 v181, s0
	v_fmamk_f32 v181, v181, 0x3a800000, v161
	v_rsq_f32_e32 v179, v181
	s_nop 0
	v_mul_f32_e32 v246, v246, v179
	v_mul_f32_e32 v8, v8, v179
	v_mul_f32_e32 v247, v247, v179
	v_mul_f32_e32 v9, v9, v179
	v_mul_f32_e32 v248, v248, v179
	v_mul_f32_e32 v10, v10, v179
	v_mul_f32_e32 v249, v249, v179
	v_mul_f32_e32 v11, v11, v179
	v_mul_f32_e32 v250, v250, v179
	v_mul_f32_e32 v12, v12, v179
	v_mul_f32_e32 v251, v251, v179
	v_mul_f32_e32 v13, v13, v179
	v_mul_f32_e32 v176, v176, v179
	v_mul_f32_e32 v14, v14, v179
	v_mul_f32_e32 v177, v177, v179
	v_mul_f32_e32 v15, v15, v179
	v_mul_f32_e32 v246, v246, v56
	v_mul_f32_e32 v8, v8, v57
	v_mul_f32_e32 v247, v247, v58
	v_mul_f32_e32 v9, v9, v59
	v_mul_f32_e32 v248, v248, v60
	v_mul_f32_e32 v10, v10, v61
	v_mul_f32_e32 v249, v249, v62
	v_mul_f32_e32 v11, v11, v63
	v_mul_f32_e32 v250, v250, v64
	v_mul_f32_e32 v12, v12, v65
	v_mul_f32_e32 v251, v251, v66
	v_mul_f32_e32 v13, v13, v67
	v_mul_f32_e32 v176, v176, v68
	v_mul_f32_e32 v14, v14, v69
	v_mul_f32_e32 v177, v177, v70
	v_mul_f32_e32 v15, v15, v71
	v_fmac_f32_e32 v238, v88, v246
	v_fmac_f32_e32 v16, v89, v8
	v_fmac_f32_e32 v239, v90, v247
	v_fmac_f32_e32 v17, v91, v9
	v_fmac_f32_e32 v240, v92, v248
	v_fmac_f32_e32 v18, v93, v10
	v_fmac_f32_e32 v241, v94, v249
	v_fmac_f32_e32 v19, v95, v11
	v_fmac_f32_e32 v242, v96, v250
	v_fmac_f32_e32 v20, v97, v12
	v_fmac_f32_e32 v243, v98, v251
	v_fmac_f32_e32 v21, v99, v13
	v_fmac_f32_e32 v244, v100, v176
	v_fmac_f32_e32 v22, v101, v14
	v_fmac_f32_e32 v245, v102, v177
	v_fmac_f32_e32 v23, v103, v15
	v_cvt_pk_bf16_f32 v120, v238, v16
	v_cvt_pk_bf16_f32 v121, v239, v17
	global_store_dwordx2 v3, v[120:121], s[4:5] offset:0 nt
	v_cvt_pk_bf16_f32 v122, v240, v18
	v_cvt_pk_bf16_f32 v123, v241, v19
	global_store_dwordx2 v3, v[122:123], s[4:5] offset:512 nt
	v_cvt_pk_bf16_f32 v124, v242, v20
	v_cvt_pk_bf16_f32 v125, v243, v21
	global_store_dwordx2 v3, v[124:125], s[4:5] offset:1024 nt
	v_cvt_pk_bf16_f32 v126, v244, v22
	v_cvt_pk_bf16_f32 v127, v245, v23
	global_store_dwordx2 v3, v[126:127], s[4:5] offset:1536 nt
	v_mul_f32_e32 v178, v238, v238
	v_fmac_f32_e32 v178, v16, v16
	v_fmac_f32_e32 v178, v239, v239
	v_fmac_f32_e32 v178, v17, v17
	v_fmac_f32_e32 v178, v240, v240
	v_fmac_f32_e32 v178, v18, v18
	v_fmac_f32_e32 v178, v241, v241
	v_fmac_f32_e32 v178, v19, v19
	v_fmac_f32_e32 v178, v242, v242
	v_fmac_f32_e32 v178, v20, v20
	v_fmac_f32_e32 v178, v243, v243
	v_fmac_f32_e32 v178, v21, v21
	v_fmac_f32_e32 v178, v244, v244
	v_fmac_f32_e32 v178, v22, v22
	v_fmac_f32_e32 v178, v245, v245
	v_fmac_f32_e32 v178, v23, v23
	s_nop 1
	v_add_f32_dpp v178, v178, v178 quad_perm:[1,0,3,2] row_mask:0xf bank_mask:0xf bound_ctrl:1
	s_nop 1
	v_add_f32_dpp v178, v178, v178 quad_perm:[2,3,0,1] row_mask:0xf bank_mask:0xf bound_ctrl:1
	s_nop 1
	v_add_f32_dpp v178, v178, v178 row_half_mirror row_mask:0xf bank_mask:0xf bound_ctrl:1
	s_nop 1
	v_add_f32_dpp v178, v178, v178 row_mirror row_mask:0xf bank_mask:0xf bound_ctrl:1
	s_nop 1
	v_add_f32_dpp v178, v178, v178 row_bcast:15 row_mask:0xa bank_mask:0xf
	s_nop 1
	v_add_f32_dpp v178, v178, v178 row_bcast:31 row_mask:0xc bank_mask:0xf
	s_nop 0
	v_readlane_b32 s0, v178, 63
	s_nop 1
	v_mov_b32_e32 v181, s0
	v_fmamk_f32 v181, v181, 0x3a800000, v161
	v_rsq_f32_e32 v180, v181
	s_nop 0
	v_mul_f32_e32 v238, v238, v180
	v_mul_f32_e32 v16, v16, v180
	v_mul_f32_e32 v239, v239, v180
	v_mul_f32_e32 v17, v17, v180
	v_mul_f32_e32 v240, v240, v180
	v_mul_f32_e32 v18, v18, v180
	v_mul_f32_e32 v241, v241, v180
	v_mul_f32_e32 v19, v19, v180
	v_mul_f32_e32 v242, v242, v180
	v_mul_f32_e32 v20, v20, v180
	v_mul_f32_e32 v243, v243, v180
	v_mul_f32_e32 v21, v21, v180
	v_mul_f32_e32 v244, v244, v180
	v_mul_f32_e32 v22, v22, v180
	v_mul_f32_e32 v245, v245, v180
	v_mul_f32_e32 v23, v23, v180
	v_mul_f32_e32 v238, v238, v72
	v_mul_f32_e32 v16, v16, v73
	v_mul_f32_e32 v239, v239, v74
	v_mul_f32_e32 v17, v17, v75
	v_mul_f32_e32 v240, v240, v76
	v_mul_f32_e32 v18, v18, v77
	v_mul_f32_e32 v241, v241, v78
	v_mul_f32_e32 v19, v19, v79
	v_mul_f32_e32 v242, v242, v80
	v_mul_f32_e32 v20, v20, v81
	v_mul_f32_e32 v243, v243, v82
	v_mul_f32_e32 v21, v21, v83
	v_mul_f32_e32 v244, v244, v84
	v_mul_f32_e32 v22, v22, v85
	v_mul_f32_e32 v245, v245, v86
	v_mul_f32_e32 v23, v23, v87
	v_fma_f32 v238, v238, v104, v134
	v_fma_f32 v16, v16, v105, v135
	v_fma_f32 v239, v239, v106, v136
	v_fma_f32 v17, v17, v107, v137
	v_fma_f32 v240, v240, v108, v138
	v_fma_f32 v18, v18, v109, v139
	v_fma_f32 v241, v241, v110, v140
	v_fma_f32 v19, v19, v111, v141
	v_fma_f32 v242, v242, v112, v142
	v_fma_f32 v20, v20, v113, v143
	v_fma_f32 v243, v243, v114, v144
	v_fma_f32 v21, v21, v115, v145
	v_fma_f32 v244, v244, v116, v146
	v_fma_f32 v22, v22, v117, v147
	v_fma_f32 v245, v245, v118, v148
	v_fma_f32 v23, v23, v119, v149
	v_cvt_pk_bf16_f32 v150, v238, v16
	v_cvt_pk_bf16_f32 v151, v239, v17
	global_store_dwordx2 v3, v[150:151], s[8:9] offset:0
	v_cvt_pk_bf16_f32 v152, v240, v18
	v_cvt_pk_bf16_f32 v153, v241, v19
	global_store_dwordx2 v3, v[152:153], s[8:9] offset:512
	v_cvt_pk_bf16_f32 v154, v242, v20
	v_cvt_pk_bf16_f32 v155, v243, v21
	global_store_dwordx2 v3, v[154:155], s[8:9] offset:1024
	v_cvt_pk_bf16_f32 v156, v244, v22
	v_cvt_pk_bf16_f32 v157, v245, v23
	global_store_dwordx2 v3, v[156:157], s[8:9] offset:1536
	s_waitcnt vmcnt(28)
	v_lshlrev_b32_e32 v246, 16, v190
	v_and_b32_e32 v190, 0xffff0000, v190
	v_lshlrev_b32_e32 v247, 16, v191
	v_and_b32_e32 v191, 0xffff0000, v191
	v_lshlrev_b32_e32 v248, 16, v192
	v_and_b32_e32 v192, 0xffff0000, v192
	v_lshlrev_b32_e32 v249, 16, v193
	v_and_b32_e32 v193, 0xffff0000, v193
	v_lshlrev_b32_e32 v250, 16, v194
	v_and_b32_e32 v194, 0xffff0000, v194
	v_lshlrev_b32_e32 v251, 16, v195
	v_and_b32_e32 v195, 0xffff0000, v195
	v_lshlrev_b32_e32 v176, 16, v196
	v_and_b32_e32 v196, 0xffff0000, v196
	v_lshlrev_b32_e32 v177, 16, v197
	v_and_b32_e32 v197, 0xffff0000, v197
	v_mul_f32_e32 v178, v246, v246
	v_fmac_f32_e32 v178, v190, v190
	v_fmac_f32_e32 v178, v247, v247
	v_fmac_f32_e32 v178, v191, v191
	v_fmac_f32_e32 v178, v248, v248
	v_fmac_f32_e32 v178, v192, v192
	v_fmac_f32_e32 v178, v249, v249
	v_fmac_f32_e32 v178, v193, v193
	v_fmac_f32_e32 v178, v250, v250
	v_fmac_f32_e32 v178, v194, v194
	v_fmac_f32_e32 v178, v251, v251
	v_fmac_f32_e32 v178, v195, v195
	v_fmac_f32_e32 v178, v176, v176
	v_fmac_f32_e32 v178, v196, v196
	v_fmac_f32_e32 v178, v177, v177
	v_fmac_f32_e32 v178, v197, v197
	s_waitcnt vmcnt(24)
	v_lshlrev_b32_e32 v238, 16, v198
	v_and_b32_e32 v198, 0xffff0000, v198
	v_add_f32_dpp v178, v178, v178 quad_perm:[1,0,3,2] row_mask:0xf bank_mask:0xf bound_ctrl:1
	v_lshlrev_b32_e32 v239, 16, v199
	v_and_b32_e32 v199, 0xffff0000, v199
	v_add_f32_dpp v178, v178, v178 quad_perm:[2,3,0,1] row_mask:0xf bank_mask:0xf bound_ctrl:1
	v_lshlrev_b32_e32 v240, 16, v200
	v_and_b32_e32 v200, 0xffff0000, v200
	v_add_f32_dpp v178, v178, v178 row_half_mirror row_mask:0xf bank_mask:0xf bound_ctrl:1
	v_lshlrev_b32_e32 v241, 16, v201
	v_and_b32_e32 v201, 0xffff0000, v201
	v_add_f32_dpp v178, v178, v178 row_mirror row_mask:0xf bank_mask:0xf bound_ctrl:1
	v_lshlrev_b32_e32 v242, 16, v202
	v_and_b32_e32 v202, 0xffff0000, v202
	v_add_f32_dpp v178, v178, v178 row_bcast:15 row_mask:0xa bank_mask:0xf
	v_lshlrev_b32_e32 v243, 16, v203
	v_and_b32_e32 v203, 0xffff0000, v203
	v_add_f32_dpp v178, v178, v178 row_bcast:31 row_mask:0xc bank_mask:0xf
	v_lshlrev_b32_e32 v244, 16, v204
	v_and_b32_e32 v204, 0xffff0000, v204
	v_lshlrev_b32_e32 v245, 16, v205
	v_and_b32_e32 v205, 0xffff0000, v205
	v_readlane_b32 s0, v178, 63
	s_nop 1
	v_mov_b32_e32 v181, s0
	v_fmamk_f32 v181, v181, 0x3a800000, v161
	v_rsq_f32_e32 v179, v181
	s_nop 0
	v_mul_f32_e32 v246, v246, v179
	v_mul_f32_e32 v190, v190, v179
	v_mul_f32_e32 v247, v247, v179
	v_mul_f32_e32 v191, v191, v179
	v_mul_f32_e32 v248, v248, v179
	v_mul_f32_e32 v192, v192, v179
	v_mul_f32_e32 v249, v249, v179
	v_mul_f32_e32 v193, v193, v179
	v_mul_f32_e32 v250, v250, v179
	v_mul_f32_e32 v194, v194, v179
	v_mul_f32_e32 v251, v251, v179
	v_mul_f32_e32 v195, v195, v179
	v_mul_f32_e32 v176, v176, v179
	v_mul_f32_e32 v196, v196, v179
	v_mul_f32_e32 v177, v177, v179
	v_mul_f32_e32 v197, v197, v179
	v_mul_f32_e32 v246, v246, v56
	v_mul_f32_e32 v190, v190, v57
	v_mul_f32_e32 v247, v247, v58
	v_mul_f32_e32 v191, v191, v59
	v_mul_f32_e32 v248, v248, v60
	v_mul_f32_e32 v192, v192, v61
	v_mul_f32_e32 v249, v249, v62
	v_mul_f32_e32 v193, v193, v63
	v_mul_f32_e32 v250, v250, v64
	v_mul_f32_e32 v194, v194, v65
	v_mul_f32_e32 v251, v251, v66
	v_mul_f32_e32 v195, v195, v67
	v_mul_f32_e32 v176, v176, v68
	v_mul_f32_e32 v196, v196, v69
	v_mul_f32_e32 v177, v177, v70
	v_mul_f32_e32 v197, v197, v71
	v_fmac_f32_e32 v238, v88, v246
	v_fmac_f32_e32 v198, v89, v190
	v_fmac_f32_e32 v239, v90, v247
	v_fmac_f32_e32 v199, v91, v191
	v_fmac_f32_e32 v240, v92, v248
	v_fmac_f32_e32 v200, v93, v192
	v_fmac_f32_e32 v241, v94, v249
	v_fmac_f32_e32 v201, v95, v193
	v_fmac_f32_e32 v242, v96, v250
	v_fmac_f32_e32 v202, v97, v194
	v_fmac_f32_e32 v243, v98, v251
	v_fmac_f32_e32 v203, v99, v195
	v_fmac_f32_e32 v244, v100, v176
	v_fmac_f32_e32 v204, v101, v196
	v_fmac_f32_e32 v245, v102, v177
	v_fmac_f32_e32 v205, v103, v197
	v_cvt_pk_bf16_f32 v120, v238, v198
	v_cvt_pk_bf16_f32 v121, v239, v199
	global_store_dwordx2 v4, v[120:121], s[4:5] offset:0 nt
	v_cvt_pk_bf16_f32 v122, v240, v200
	v_cvt_pk_bf16_f32 v123, v241, v201
	global_store_dwordx2 v4, v[122:123], s[4:5] offset:512 nt
	v_cvt_pk_bf16_f32 v124, v242, v202
	v_cvt_pk_bf16_f32 v125, v243, v203
	global_store_dwordx2 v4, v[124:125], s[4:5] offset:1024 nt
	v_cvt_pk_bf16_f32 v126, v244, v204
	v_cvt_pk_bf16_f32 v127, v245, v205
	global_store_dwordx2 v4, v[126:127], s[4:5] offset:1536 nt
	v_mul_f32_e32 v178, v238, v238
	v_fmac_f32_e32 v178, v198, v198
	v_fmac_f32_e32 v178, v239, v239
	v_fmac_f32_e32 v178, v199, v199
	v_fmac_f32_e32 v178, v240, v240
	v_fmac_f32_e32 v178, v200, v200
	v_fmac_f32_e32 v178, v241, v241
	v_fmac_f32_e32 v178, v201, v201
	v_fmac_f32_e32 v178, v242, v242
	v_fmac_f32_e32 v178, v202, v202
	v_fmac_f32_e32 v178, v243, v243
	v_fmac_f32_e32 v178, v203, v203
	v_fmac_f32_e32 v178, v244, v244
	v_fmac_f32_e32 v178, v204, v204
	v_fmac_f32_e32 v178, v245, v245
	v_fmac_f32_e32 v178, v205, v205
	s_nop 1
	v_add_f32_dpp v178, v178, v178 quad_perm:[1,0,3,2] row_mask:0xf bank_mask:0xf bound_ctrl:1
	s_nop 1
	v_add_f32_dpp v178, v178, v178 quad_perm:[2,3,0,1] row_mask:0xf bank_mask:0xf bound_ctrl:1
	s_nop 1
	v_add_f32_dpp v178, v178, v178 row_half_mirror row_mask:0xf bank_mask:0xf bound_ctrl:1
	s_nop 1
	v_add_f32_dpp v178, v178, v178 row_mirror row_mask:0xf bank_mask:0xf bound_ctrl:1
	s_nop 1
	v_add_f32_dpp v178, v178, v178 row_bcast:15 row_mask:0xa bank_mask:0xf
	s_nop 1
	v_add_f32_dpp v178, v178, v178 row_bcast:31 row_mask:0xc bank_mask:0xf
	s_nop 0
	v_readlane_b32 s0, v178, 63
	s_nop 1
	v_mov_b32_e32 v181, s0
	v_fmamk_f32 v181, v181, 0x3a800000, v161
	v_rsq_f32_e32 v180, v181
	s_nop 0
	v_mul_f32_e32 v238, v238, v180
	v_mul_f32_e32 v198, v198, v180
	v_mul_f32_e32 v239, v239, v180
	v_mul_f32_e32 v199, v199, v180
	v_mul_f32_e32 v240, v240, v180
	v_mul_f32_e32 v200, v200, v180
	v_mul_f32_e32 v241, v241, v180
	v_mul_f32_e32 v201, v201, v180
	v_mul_f32_e32 v242, v242, v180
	v_mul_f32_e32 v202, v202, v180
	v_mul_f32_e32 v243, v243, v180
	v_mul_f32_e32 v203, v203, v180
	v_mul_f32_e32 v244, v244, v180
	v_mul_f32_e32 v204, v204, v180
	v_mul_f32_e32 v245, v245, v180
	v_mul_f32_e32 v205, v205, v180
	v_mul_f32_e32 v238, v238, v72
	v_mul_f32_e32 v198, v198, v73
	v_mul_f32_e32 v239, v239, v74
	v_mul_f32_e32 v199, v199, v75
	v_mul_f32_e32 v240, v240, v76
	v_mul_f32_e32 v200, v200, v77
	v_mul_f32_e32 v241, v241, v78
	v_mul_f32_e32 v201, v201, v79
	v_mul_f32_e32 v242, v242, v80
	v_mul_f32_e32 v202, v202, v81
	v_mul_f32_e32 v243, v243, v82
	v_mul_f32_e32 v203, v203, v83
	v_mul_f32_e32 v244, v244, v84
	v_mul_f32_e32 v204, v204, v85
	v_mul_f32_e32 v245, v245, v86
	v_mul_f32_e32 v205, v205, v87
	v_fma_f32 v238, v238, v104, v134
	v_fma_f32 v198, v198, v105, v135
	v_fma_f32 v239, v239, v106, v136
	v_fma_f32 v199, v199, v107, v137
	v_fma_f32 v240, v240, v108, v138
	v_fma_f32 v200, v200, v109, v139
	v_fma_f32 v241, v241, v110, v140
	v_fma_f32 v201, v201, v111, v141
	v_fma_f32 v242, v242, v112, v142
	v_fma_f32 v202, v202, v113, v143
	v_fma_f32 v243, v243, v114, v144
	v_fma_f32 v203, v203, v115, v145
	v_fma_f32 v244, v244, v116, v146
	v_fma_f32 v204, v204, v117, v147
	v_fma_f32 v245, v245, v118, v148
	v_fma_f32 v205, v205, v119, v149
	v_cvt_pk_bf16_f32 v150, v238, v198
	v_cvt_pk_bf16_f32 v151, v239, v199
	global_store_dwordx2 v4, v[150:151], s[8:9] offset:0
	v_cvt_pk_bf16_f32 v152, v240, v200
	v_cvt_pk_bf16_f32 v153, v241, v201
	global_store_dwordx2 v4, v[152:153], s[8:9] offset:512
	v_cvt_pk_bf16_f32 v154, v242, v202
	v_cvt_pk_bf16_f32 v155, v243, v203
	global_store_dwordx2 v4, v[154:155], s[8:9] offset:1024
	v_cvt_pk_bf16_f32 v156, v244, v204
	v_cvt_pk_bf16_f32 v157, v245, v205
	global_store_dwordx2 v4, v[156:157], s[8:9] offset:1536
	s_branch .LBB0_100
.Lrow2_last:
	v_readfirstlane_b32 s0, v160
	v_readlane_b32 s1, v252, 7
	s_lshr_b32 s0, s0, 6
	s_mov_b32 s73, s0
	s_add_i32 s0, s0, s1
	v_readlane_b32 s62, v254, 34
	s_sub_u32 s64, s78, 0x110
	s_subb_u32 s65, s79, 0
	s_load_dwordx2 s[66:67], s[64:65], 0x40
	s_load_dwordx2 s[10:11], s[64:65], 0xf8
	s_lshl_b32 s63, s0, 11
	s_add_u32 s4, s84, 0x167ca000
	s_addc_u32 s5, s85, 0
	s_add_u32 s4, s4, s63
	s_addc_u32 s5, s5, 0
	s_add_u32 s6, s84, 0x112ca000
	s_addc_u32 s7, s85, 0
	s_add_u32 s6, s6, s63
	s_addc_u32 s7, s7, 0
	v_and_b32_e32 v0, 63, v160
	v_lshlrev_b32_e32 v1, 4, v0
	v_lshlrev_b32_e32 v0, 3, v0
	v_add_u32_e32 v2, 0x400000, v0
	v_add_u32_e32 v3, 0x800000, v0
	v_add_u32_e32 v4, 0xc00000, v0
	v_add_u32_e32 v5, 0x1000000, v0
	global_load_dwordx2 v[8:9], v5, s[6:7] offset:0 nt
	global_load_dwordx2 v[10:11], v5, s[6:7] offset:512 nt
	global_load_dwordx2 v[12:13], v5, s[6:7] offset:1024 nt
	global_load_dwordx2 v[14:15], v5, s[6:7] offset:1536 nt
	global_load_dwordx2 v[16:17], v5, s[4:5] offset:0 nt
	global_load_dwordx2 v[18:19], v5, s[4:5] offset:512 nt
	global_load_dwordx2 v[20:21], v5, s[4:5] offset:1024 nt
	global_load_dwordx2 v[22:23], v5, s[4:5] offset:1536 nt
	s_add_u32 s8, s84, 0xaeca000
	s_addc_u32 s9, s85, 0
	s_add_u32 s8, s8, s63
	s_addc_u32 s9, s9, 0
	s_lshr_b32 s69, s0, 10
	s_add_i32 s69, s69, 1
	s_mul_i32 s69, s69, 0x6000
	s_mul_i32 s68, s62, 0x12000
	s_mov_b32 s70, 0
	s_mul_i32 s71, s70, 0x12000
	s_lshl_b32 s70, s70, 14
	s_lshl_b32 s72, s62, 14
	s_add_i32 s72, s72, 0x3000
	s_add_u32 s16, s84, 0x6605000
	s_addc_u32 s17, s85, 0
	s_add_u32 s16, s16, s68
	s_addc_u32 s17, s17, 0
	s_add_u32 s20, s84, 0x6600000
	s_addc_u32 s21, s85, 0
	s_add_u32 s20, s20, s71
	s_addc_u32 s21, s21, 0
	s_add_u32 s18, s20, 0x1000
	s_addc_u32 s19, s21, 0
	s_add_u32 s22, s16, s69
	s_addc_u32 s23, s17, 0
	s_add_u32 s60, s20, s69
	s_addc_u32 s61, s21, 0
	s_add_u32 s26, s18, s69
	s_addc_u32 s27, s19, 0
	s_lshl_b32 s63, s63, 1
	s_waitcnt lgkmcnt(0)
	s_add_u32 s12, s66, s72
	s_addc_u32 s13, s67, 0
	s_add_u32 s14, s66, s70
	s_addc_u32 s15, s67, 0
	s_add_u32 s10, s10, s63
	s_addc_u32 s11, s11, 0
	s_mov_b64 s[74:75], s[12:13]
	s_cmp_eq_u32 s73, 1
	s_cselect_b32 s74, s14, s74
	s_cselect_b32 s75, s15, s75
	s_cmp_eq_u32 s73, 2
	s_cselect_b32 s74, s16, s74
	s_cselect_b32 s75, s17, s75
	s_cmp_eq_u32 s73, 3
	s_cselect_b32 s74, s18, s74
	s_cselect_b32 s75, s19, s75
	s_cmp_eq_u32 s73, 4
	s_cselect_b32 s74, s20, s74
	s_cselect_b32 s75, s21, s75
	s_cmp_eq_u32 s73, 5
	s_cselect_b32 s74, s22, s74
	s_cselect_b32 s75, s23, s75
	s_cmp_eq_u32 s73, 6
	s_cselect_b32 s74, s26, s74
	s_cselect_b32 s75, s27, s75
	s_cmp_eq_u32 s73, 7
	s_cselect_b32 s74, s60, s74
	s_cselect_b32 s75, s61, s75
	global_load_dwordx4 v[222:225], v1, s[74:75] offset:0
	global_load_dwordx4 v[226:229], v1, s[74:75] offset:1024
	global_load_dwordx4 v[230:233], v1, s[74:75] offset:2048
	global_load_dwordx4 v[234:237], v1, s[74:75] offset:3072
	s_lshl_b32 s74, s73, 12
	v_add_u32_e32 v6, s74, v1
	global_load_dwordx2 v[24:25], v0, s[6:7] offset:0 nt
	global_load_dwordx2 v[26:27], v0, s[6:7] offset:512 nt
	global_load_dwordx2 v[28:29], v0, s[6:7] offset:1024 nt
	global_load_dwordx2 v[30:31], v0, s[6:7] offset:1536 nt
	global_load_dwordx2 v[32:33], v0, s[4:5] offset:0 nt
	global_load_dwordx2 v[34:35], v0, s[4:5] offset:512 nt
	global_load_dwordx2 v[36:37], v0, s[4:5] offset:1024 nt
	global_load_dwordx2 v[38:39], v0, s[4:5] offset:1536 nt
	global_load_dwordx2 v[40:41], v2, s[6:7] offset:0 nt
	global_load_dwordx2 v[42:43], v2, s[6:7] offset:512 nt
	global_load_dwordx2 v[44:45], v2, s[6:7] offset:1024 nt
	global_load_dwordx2 v[46:47], v2, s[6:7] offset:1536 nt
	global_load_dwordx2 v[48:49], v2, s[4:5] offset:0 nt
	global_load_dwordx2 v[50:51], v2, s[4:5] offset:512 nt
	global_load_dwordx2 v[52:53], v2, s[4:5] offset:1024 nt
	global_load_dwordx2 v[54:55], v2, s[4:5] offset:1536 nt
	s_waitcnt vmcnt(16)
	ds_write_b128 v6, v[222:225] offset:0
	ds_write_b128 v6, v[226:229] offset:1024
	ds_write_b128 v6, v[230:233] offset:2048
	ds_write_b128 v6, v[234:237] offset:3072
	s_waitcnt lgkmcnt(0)
	s_barrier
	ds_read_b128 v[56:59], v1 offset:0
	ds_read_b128 v[60:63], v1 offset:1024
	ds_read_b128 v[64:67], v1 offset:2048
	ds_read_b128 v[68:71], v1 offset:3072
	ds_read_b128 v[88:91], v1 offset:8192
	ds_read_b128 v[92:95], v1 offset:9216
	ds_read_b128 v[96:99], v1 offset:10240
	ds_read_b128 v[100:103], v1 offset:11264
	ds_read_b128 v[190:193], v1 offset:20480
	ds_read_b128 v[194:197], v1 offset:21504
	ds_read_b128 v[198:201], v1 offset:22528
	ds_read_b128 v[202:205], v1 offset:23552
	v_lshlrev_b32_e32 v246, 16, v8
	v_and_b32_e32 v8, 0xffff0000, v8
	v_lshlrev_b32_e32 v247, 16, v9
	v_and_b32_e32 v9, 0xffff0000, v9
	v_lshlrev_b32_e32 v248, 16, v10
	v_and_b32_e32 v10, 0xffff0000, v10
	v_lshlrev_b32_e32 v249, 16, v11
	v_and_b32_e32 v11, 0xffff0000, v11
	v_lshlrev_b32_e32 v250, 16, v12
	v_and_b32_e32 v12, 0xffff0000, v12
	v_lshlrev_b32_e32 v251, 16, v13
	v_and_b32_e32 v13, 0xffff0000, v13
	v_lshlrev_b32_e32 v176, 16, v14
	v_and_b32_e32 v14, 0xffff0000, v14
	v_lshlrev_b32_e32 v177, 16, v15
	v_and_b32_e32 v15, 0xffff0000, v15
	v_mul_f32_e32 v178, v246, v246
	v_fmac_f32_e32 v178, v8, v8
	v_fmac_f32_e32 v178, v247, v247
	v_fmac_f32_e32 v178, v9, v9
	v_fmac_f32_e32 v178, v248, v248
	v_fmac_f32_e32 v178, v10, v10
	v_fmac_f32_e32 v178, v249, v249
	v_fmac_f32_e32 v178, v11, v11
	v_fmac_f32_e32 v178, v250, v250
	v_fmac_f32_e32 v178, v12, v12
	v_fmac_f32_e32 v178, v251, v251
	v_fmac_f32_e32 v178, v13, v13
	v_fmac_f32_e32 v178, v176, v176
	v_fmac_f32_e32 v178, v14, v14
	v_fmac_f32_e32 v178, v177, v177
	v_fmac_f32_e32 v178, v15, v15
	v_lshlrev_b32_e32 v238, 16, v16
	v_and_b32_e32 v16, 0xffff0000, v16
	v_add_f32_dpp v178, v178, v178 quad_perm:[1,0,3,2] row_mask:0xf bank_mask:0xf bound_ctrl:1
	v_lshlrev_b32_e32 v239, 16, v17
	v_and_b32_e32 v17, 0xffff0000, v17
	v_add_f32_dpp v178, v178, v178 quad_perm:[2,3,0,1] row_mask:0xf bank_mask:0xf bound_ctrl:1
	v_lshlrev_b32_e32 v240, 16, v18
	v_and_b32_e32 v18, 0xffff0000, v18
	v_add_f32_dpp v178, v178, v178 row_half_mirror row_mask:0xf bank_mask:0xf bound_ctrl:1
	v_lshlrev_b32_e32 v241, 16, v19
	v_and_b32_e32 v19, 0xffff0000, v19
	v_add_f32_dpp v178, v178, v178 row_mirror row_mask:0xf bank_mask:0xf bound_ctrl:1
	v_lshlrev_b32_e32 v242, 16, v20
	v_and_b32_e32 v20, 0xffff0000, v20
	v_add_f32_dpp v178, v178, v178 row_bcast:15 row_mask:0xa bank_mask:0xf
	v_lshlrev_b32_e32 v243, 16, v21
	v_and_b32_e32 v21, 0xffff0000, v21
	v_add_f32_dpp v178, v178, v178 row_bcast:31 row_mask:0xc bank_mask:0xf
	v_lshlrev_b32_e32 v244, 16, v22
	v_and_b32_e32 v22, 0xffff0000, v22
	v_lshlrev_b32_e32 v245, 16, v23
	v_and_b32_e32 v23, 0xffff0000, v23
	v_readlane_b32 s0, v178, 63
	s_nop 1
	v_mov_b32_e32 v181, s0
	v_fmamk_f32 v181, v181, 0x3a800000, v161
	v_rsq_f32_e32 v179, v181
	s_nop 0
	s_waitcnt lgkmcnt(0)
	v_mul_f32_e32 v246, v246, v179
	v_mul_f32_e32 v8, v8, v179
	v_mul_f32_e32 v247, v247, v179
	v_mul_f32_e32 v9, v9, v179
	v_mul_f32_e32 v248, v248, v179
	v_mul_f32_e32 v10, v10, v179
	v_mul_f32_e32 v249, v249, v179
	v_mul_f32_e32 v11, v11, v179
	v_mul_f32_e32 v250, v250, v179
	v_mul_f32_e32 v12, v12, v179
	v_mul_f32_e32 v251, v251, v179
	v_mul_f32_e32 v13, v13, v179
	v_mul_f32_e32 v176, v176, v179
	v_mul_f32_e32 v14, v14, v179
	v_mul_f32_e32 v177, v177, v179
	v_mul_f32_e32 v15, v15, v179
	v_mul_f32_e32 v246, v246, v56
	v_mul_f32_e32 v8, v8, v57
	v_mul_f32_e32 v247, v247, v58
	v_mul_f32_e32 v9, v9, v59
	v_mul_f32_e32 v248, v248, v60
	v_mul_f32_e32 v10, v10, v61
	v_mul_f32_e32 v249, v249, v62
	v_mul_f32_e32 v11, v11, v63
	v_mul_f32_e32 v250, v250, v64
	v_mul_f32_e32 v12, v12, v65
	v_mul_f32_e32 v251, v251, v66
	v_mul_f32_e32 v13, v13, v67
	v_mul_f32_e32 v176, v176, v68
	v_mul_f32_e32 v14, v14, v69
	v_mul_f32_e32 v177, v177, v70
	v_mul_f32_e32 v15, v15, v71
	v_fmac_f32_e32 v238, v190, v246
	v_fmac_f32_e32 v16, v191, v8
	v_fmac_f32_e32 v239, v192, v247
	v_fmac_f32_e32 v17, v193, v9
	v_fmac_f32_e32 v240, v194, v248
	v_fmac_f32_e32 v18, v195, v10
	v_fmac_f32_e32 v241, v196, v249
	v_fmac_f32_e32 v19, v197, v11
	v_fmac_f32_e32 v242, v198, v250
	v_fmac_f32_e32 v20, v199, v12
	v_fmac_f32_e32 v243, v200, v251
	v_fmac_f32_e32 v21, v201, v13
	v_fmac_f32_e32 v244, v202, v176
	v_fmac_f32_e32 v22, v203, v14
	v_fmac_f32_e32 v245, v204, v177
	v_fmac_f32_e32 v23, v205, v15
	v_add_u32_e32 v181, 0x2000000, v1
	v_mov_b32_e32 v120, v238
	v_mov_b32_e32 v121, v16
	v_mov_b32_e32 v122, v239
	v_mov_b32_e32 v123, v17
	global_store_dwordx4 v181, v[120:123], s[10:11] offset:0
	v_mov_b32_e32 v124, v240
	v_mov_b32_e32 v125, v18
	v_mov_b32_e32 v126, v241
	v_mov_b32_e32 v127, v19
	global_store_dwordx4 v181, v[124:127], s[10:11] offset:1024
	v_mov_b32_e32 v150, v242
	v_mov_b32_e32 v151, v20
	v_mov_b32_e32 v152, v243
	v_mov_b32_e32 v153, v21
	global_store_dwordx4 v181, v[150:153], s[10:11] offset:2048
	v_mov_b32_e32 v154, v244
	v_mov_b32_e32 v155, v22
	v_mov_b32_e32 v156, v245
	v_mov_b32_e32 v157, v23
	global_store_dwordx4 v181, v[154:157], s[10:11] offset:3072
	global_load_dwordx2 v[8:9], v3, s[6:7] offset:0 nt
	global_load_dwordx2 v[10:11], v3, s[6:7] offset:512 nt
	global_load_dwordx2 v[12:13], v3, s[6:7] offset:1024 nt
	global_load_dwordx2 v[14:15], v3, s[6:7] offset:1536 nt
	global_load_dwordx2 v[16:17], v3, s[4:5] offset:0 nt
	global_load_dwordx2 v[18:19], v3, s[4:5] offset:512 nt
	global_load_dwordx2 v[20:21], v3, s[4:5] offset:1024 nt
	global_load_dwordx2 v[22:23], v3, s[4:5] offset:1536 nt
	global_load_dwordx2 v[190:191], v4, s[6:7] offset:0 nt
	global_load_dwordx2 v[192:193], v4, s[6:7] offset:512 nt
	global_load_dwordx2 v[194:195], v4, s[6:7] offset:1024 nt
	global_load_dwordx2 v[196:197], v4, s[6:7] offset:1536 nt
	global_load_dwordx2 v[198:199], v4, s[4:5] offset:0 nt
	global_load_dwordx2 v[200:201], v4, s[4:5] offset:512 nt
	global_load_dwordx2 v[202:203], v4, s[4:5] offset:1024 nt
	global_load_dwordx2 v[204:205], v4, s[4:5] offset:1536 nt
	s_waitcnt vmcnt(32)
	v_lshlrev_b32_e32 v246, 16, v24
	v_and_b32_e32 v24, 0xffff0000, v24
	v_lshlrev_b32_e32 v247, 16, v25
	v_and_b32_e32 v25, 0xffff0000, v25
	v_lshlrev_b32_e32 v248, 16, v26
	v_and_b32_e32 v26, 0xffff0000, v26
	v_lshlrev_b32_e32 v249, 16, v27
	v_and_b32_e32 v27, 0xffff0000, v27
	v_lshlrev_b32_e32 v250, 16, v28
	v_and_b32_e32 v28, 0xffff0000, v28
	v_lshlrev_b32_e32 v251, 16, v29
	v_and_b32_e32 v29, 0xffff0000, v29
	v_lshlrev_b32_e32 v176, 16, v30
	v_and_b32_e32 v30, 0xffff0000, v30
	v_lshlrev_b32_e32 v177, 16, v31
	v_and_b32_e32 v31, 0xffff0000, v31
	v_mul_f32_e32 v178, v246, v246
	v_fmac_f32_e32 v178, v24, v24
	v_fmac_f32_e32 v178, v247, v247
	v_fmac_f32_e32 v178, v25, v25
	v_fmac_f32_e32 v178, v248, v248
	v_fmac_f32_e32 v178, v26, v26
	v_fmac_f32_e32 v178, v249, v249
	v_fmac_f32_e32 v178, v27, v27
	v_fmac_f32_e32 v178, v250, v250
	v_fmac_f32_e32 v178, v28, v28
	v_fmac_f32_e32 v178, v251, v251
	v_fmac_f32_e32 v178, v29, v29
	v_fmac_f32_e32 v178, v176, v176
	v_fmac_f32_e32 v178, v30, v30
	v_fmac_f32_e32 v178, v177, v177
	v_fmac_f32_e32 v178, v31, v31
	s_waitcnt vmcnt(28)
	v_lshlrev_b32_e32 v238, 16, v32
	v_and_b32_e32 v32, 0xffff0000, v32
	v_add_f32_dpp v178, v178, v178 quad_perm:[1,0,3,2] row_mask:0xf bank_mask:0xf bound_ctrl:1
	v_lshlrev_b32_e32 v239, 16, v33
	v_and_b32_e32 v33, 0xffff0000, v33
	v_add_f32_dpp v178, v178, v178 quad_perm:[2,3,0,1] row_mask:0xf bank_mask:0xf bound_ctrl:1
	v_lshlrev_b32_e32 v240, 16, v34
	v_and_b32_e32 v34, 0xffff0000, v34
	v_add_f32_dpp v178, v178, v178 row_half_mirror row_mask:0xf bank_mask:0xf bound_ctrl:1
	v_lshlrev_b32_e32 v241, 16, v35
	v_and_b32_e32 v35, 0xffff0000, v35
	v_add_f32_dpp v178, v178, v178 row_mirror row_mask:0xf bank_mask:0xf bound_ctrl:1
	v_lshlrev_b32_e32 v242, 16, v36
	v_and_b32_e32 v36, 0xffff0000, v36
	v_add_f32_dpp v178, v178, v178 row_bcast:15 row_mask:0xa bank_mask:0xf
	v_lshlrev_b32_e32 v243, 16, v37
	v_and_b32_e32 v37, 0xffff0000, v37
	v_add_f32_dpp v178, v178, v178 row_bcast:31 row_mask:0xc bank_mask:0xf
	v_lshlrev_b32_e32 v244, 16, v38
	v_and_b32_e32 v38, 0xffff0000, v38
	v_lshlrev_b32_e32 v245, 16, v39
	v_and_b32_e32 v39, 0xffff0000, v39
	v_readlane_b32 s0, v178, 63
	s_nop 1
	v_mov_b32_e32 v181, s0
	v_fmamk_f32 v181, v181, 0x3a800000, v161
	v_rsq_f32_e32 v179, v181
	s_nop 0
	v_mul_f32_e32 v246, v246, v179
	v_mul_f32_e32 v24, v24, v179
	v_mul_f32_e32 v247, v247, v179
	v_mul_f32_e32 v25, v25, v179
	v_mul_f32_e32 v248, v248, v179
	v_mul_f32_e32 v26, v26, v179
	v_mul_f32_e32 v249, v249, v179
	v_mul_f32_e32 v27, v27, v179
	v_mul_f32_e32 v250, v250, v179
	v_mul_f32_e32 v28, v28, v179
	v_mul_f32_e32 v251, v251, v179
	v_mul_f32_e32 v29, v29, v179
	v_mul_f32_e32 v176, v176, v179
	v_mul_f32_e32 v30, v30, v179
	v_mul_f32_e32 v177, v177, v179
	v_mul_f32_e32 v31, v31, v179
	v_mul_f32_e32 v246, v246, v56
	v_mul_f32_e32 v24, v24, v57
	v_mul_f32_e32 v247, v247, v58
	v_mul_f32_e32 v25, v25, v59
	v_mul_f32_e32 v248, v248, v60
	v_mul_f32_e32 v26, v26, v61
	v_mul_f32_e32 v249, v249, v62
	v_mul_f32_e32 v27, v27, v63
	v_mul_f32_e32 v250, v250, v64
	v_mul_f32_e32 v28, v28, v65
	v_mul_f32_e32 v251, v251, v66
	v_mul_f32_e32 v29, v29, v67
	v_mul_f32_e32 v176, v176, v68
	v_mul_f32_e32 v30, v30, v69
	v_mul_f32_e32 v177, v177, v70
	v_mul_f32_e32 v31, v31, v71
	v_fmac_f32_e32 v238, v88, v246
	v_fmac_f32_e32 v32, v89, v24
	v_fmac_f32_e32 v239, v90, v247
	v_fmac_f32_e32 v33, v91, v25
	v_fmac_f32_e32 v240, v92, v248
	v_fmac_f32_e32 v34, v93, v26
	v_fmac_f32_e32 v241, v94, v249
	v_fmac_f32_e32 v35, v95, v27
	v_fmac_f32_e32 v242, v96, v250
	v_fmac_f32_e32 v36, v97, v28
	v_fmac_f32_e32 v243, v98, v251
	v_fmac_f32_e32 v37, v99, v29
	v_fmac_f32_e32 v244, v100, v176
	v_fmac_f32_e32 v38, v101, v30
	v_fmac_f32_e32 v245, v102, v177
	v_fmac_f32_e32 v39, v103, v31
	v_add_u32_e32 v181, 0x0, v1
	v_mov_b32_e32 v120, v238
	v_mov_b32_e32 v121, v32
	v_mov_b32_e32 v122, v239
	v_mov_b32_e32 v123, v33
	global_store_dwordx4 v181, v[120:123], s[10:11] offset:0
	v_mov_b32_e32 v124, v240
	v_mov_b32_e32 v125, v34
	v_mov_b32_e32 v126, v241
	v_mov_b32_e32 v127, v35
	global_store_dwordx4 v181, v[124:127], s[10:11] offset:1024
	v_mov_b32_e32 v150, v242
	v_mov_b32_e32 v151, v36
	v_mov_b32_e32 v152, v243
	v_mov_b32_e32 v153, v37
	global_store_dwordx4 v181, v[150:153], s[10:11] offset:2048
	v_mov_b32_e32 v154, v244
	v_mov_b32_e32 v155, v38
	v_mov_b32_e32 v156, v245
	v_mov_b32_e32 v157, v39
	global_store_dwordx4 v181, v[154:157], s[10:11] offset:3072
	s_waitcnt vmcnt(28)
	v_lshlrev_b32_e32 v246, 16, v40
	v_and_b32_e32 v40, 0xffff0000, v40
	v_lshlrev_b32_e32 v247, 16, v41
	v_and_b32_e32 v41, 0xffff0000, v41
	v_lshlrev_b32_e32 v248, 16, v42
	v_and_b32_e32 v42, 0xffff0000, v42
	v_lshlrev_b32_e32 v249, 16, v43
	v_and_b32_e32 v43, 0xffff0000, v43
	v_lshlrev_b32_e32 v250, 16, v44
	v_and_b32_e32 v44, 0xffff0000, v44
	v_lshlrev_b32_e32 v251, 16, v45
	v_and_b32_e32 v45, 0xffff0000, v45
	v_lshlrev_b32_e32 v176, 16, v46
	v_and_b32_e32 v46, 0xffff0000, v46
	v_lshlrev_b32_e32 v177, 16, v47
	v_and_b32_e32 v47, 0xffff0000, v47
	v_mul_f32_e32 v178, v246, v246
	v_fmac_f32_e32 v178, v40, v40
	v_fmac_f32_e32 v178, v247, v247
	v_fmac_f32_e32 v178, v41, v41
	v_fmac_f32_e32 v178, v248, v248
	v_fmac_f32_e32 v178, v42, v42
	v_fmac_f32_e32 v178, v249, v249
	v_fmac_f32_e32 v178, v43, v43
	v_fmac_f32_e32 v178, v250, v250
	v_fmac_f32_e32 v178, v44, v44
	v_fmac_f32_e32 v178, v251, v251
	v_fmac_f32_e32 v178, v45, v45
	v_fmac_f32_e32 v178, v176, v176
	v_fmac_f32_e32 v178, v46, v46
	v_fmac_f32_e32 v178, v177, v177
	v_fmac_f32_e32 v178, v47, v47
	s_waitcnt vmcnt(24)
	v_lshlrev_b32_e32 v238, 16, v48
	v_and_b32_e32 v48, 0xffff0000, v48
	v_add_f32_dpp v178, v178, v178 quad_perm:[1,0,3,2] row_mask:0xf bank_mask:0xf bound_ctrl:1
	v_lshlrev_b32_e32 v239, 16, v49
	v_and_b32_e32 v49, 0xffff0000, v49
	v_add_f32_dpp v178, v178, v178 quad_perm:[2,3,0,1] row_mask:0xf bank_mask:0xf bound_ctrl:1
	v_lshlrev_b32_e32 v240, 16, v50
	v_and_b32_e32 v50, 0xffff0000, v50
	v_add_f32_dpp v178, v178, v178 row_half_mirror row_mask:0xf bank_mask:0xf bound_ctrl:1
	v_lshlrev_b32_e32 v241, 16, v51
	v_and_b32_e32 v51, 0xffff0000, v51
	v_add_f32_dpp v178, v178, v178 row_mirror row_mask:0xf bank_mask:0xf bound_ctrl:1
	v_lshlrev_b32_e32 v242, 16, v52
	v_and_b32_e32 v52, 0xffff0000, v52
	v_add_f32_dpp v178, v178, v178 row_bcast:15 row_mask:0xa bank_mask:0xf
	v_lshlrev_b32_e32 v243, 16, v53
	v_and_b32_e32 v53, 0xffff0000, v53
	v_add_f32_dpp v178, v178, v178 row_bcast:31 row_mask:0xc bank_mask:0xf
	v_lshlrev_b32_e32 v244, 16, v54
	v_and_b32_e32 v54, 0xffff0000, v54
	v_lshlrev_b32_e32 v245, 16, v55
	v_and_b32_e32 v55, 0xffff0000, v55
	v_readlane_b32 s0, v178, 63
	s_nop 1
	v_mov_b32_e32 v181, s0
	v_fmamk_f32 v181, v181, 0x3a800000, v161
	v_rsq_f32_e32 v179, v181
	s_nop 0
	v_mul_f32_e32 v246, v246, v179
	v_mul_f32_e32 v40, v40, v179
	v_mul_f32_e32 v247, v247, v179
	v_mul_f32_e32 v41, v41, v179
	v_mul_f32_e32 v248, v248, v179
	v_mul_f32_e32 v42, v42, v179
	v_mul_f32_e32 v249, v249, v179
	v_mul_f32_e32 v43, v43, v179
	v_mul_f32_e32 v250, v250, v179
	v_mul_f32_e32 v44, v44, v179
	v_mul_f32_e32 v251, v251, v179
	v_mul_f32_e32 v45, v45, v179
	v_mul_f32_e32 v176, v176, v179
	v_mul_f32_e32 v46, v46, v179
	v_mul_f32_e32 v177, v177, v179
	v_mul_f32_e32 v47, v47, v179
	v_mul_f32_e32 v246, v246, v56
	v_mul_f32_e32 v40, v40, v57
	v_mul_f32_e32 v247, v247, v58
	v_mul_f32_e32 v41, v41, v59
	v_mul_f32_e32 v248, v248, v60
	v_mul_f32_e32 v42, v42, v61
	v_mul_f32_e32 v249, v249, v62
	v_mul_f32_e32 v43, v43, v63
	v_mul_f32_e32 v250, v250, v64
	v_mul_f32_e32 v44, v44, v65
	v_mul_f32_e32 v251, v251, v66
	v_mul_f32_e32 v45, v45, v67
	v_mul_f32_e32 v176, v176, v68
	v_mul_f32_e32 v46, v46, v69
	v_mul_f32_e32 v177, v177, v70
	v_mul_f32_e32 v47, v47, v71
	v_fmac_f32_e32 v238, v88, v246
	v_fmac_f32_e32 v48, v89, v40
	v_fmac_f32_e32 v239, v90, v247
	v_fmac_f32_e32 v49, v91, v41
	v_fmac_f32_e32 v240, v92, v248
	v_fmac_f32_e32 v50, v93, v42
	v_fmac_f32_e32 v241, v94, v249
	v_fmac_f32_e32 v51, v95, v43
	v_fmac_f32_e32 v242, v96, v250
	v_fmac_f32_e32 v52, v97, v44
	v_fmac_f32_e32 v243, v98, v251
	v_fmac_f32_e32 v53, v99, v45
	v_fmac_f32_e32 v244, v100, v176
	v_fmac_f32_e32 v54, v101, v46
	v_fmac_f32_e32 v245, v102, v177
	v_fmac_f32_e32 v55, v103, v47
	v_add_u32_e32 v181, 0x800000, v1
	v_mov_b32_e32 v120, v238
	v_mov_b32_e32 v121, v48
	v_mov_b32_e32 v122, v239
	v_mov_b32_e32 v123, v49
	global_store_dwordx4 v181, v[120:123], s[10:11] offset:0
	v_mov_b32_e32 v124, v240
	v_mov_b32_e32 v125, v50
	v_mov_b32_e32 v126, v241
	v_mov_b32_e32 v127, v51
	global_store_dwordx4 v181, v[124:127], s[10:11] offset:1024
	v_mov_b32_e32 v150, v242
	v_mov_b32_e32 v151, v52
	v_mov_b32_e32 v152, v243
	v_mov_b32_e32 v153, v53
	global_store_dwordx4 v181, v[150:153], s[10:11] offset:2048
	v_mov_b32_e32 v154, v244
	v_mov_b32_e32 v155, v54
	v_mov_b32_e32 v156, v245
	v_mov_b32_e32 v157, v55
	global_store_dwordx4 v181, v[154:157], s[10:11] offset:3072
	s_waitcnt vmcnt(20)
	v_lshlrev_b32_e32 v246, 16, v8
	v_and_b32_e32 v8, 0xffff0000, v8
	v_lshlrev_b32_e32 v247, 16, v9
	v_and_b32_e32 v9, 0xffff0000, v9
	v_lshlrev_b32_e32 v248, 16, v10
	v_and_b32_e32 v10, 0xffff0000, v10
	v_lshlrev_b32_e32 v249, 16, v11
	v_and_b32_e32 v11, 0xffff0000, v11
	v_lshlrev_b32_e32 v250, 16, v12
	v_and_b32_e32 v12, 0xffff0000, v12
	v_lshlrev_b32_e32 v251, 16, v13
	v_and_b32_e32 v13, 0xffff0000, v13
	v_lshlrev_b32_e32 v176, 16, v14
	v_and_b32_e32 v14, 0xffff0000, v14
	v_lshlrev_b32_e32 v177, 16, v15
	v_and_b32_e32 v15, 0xffff0000, v15
	v_mul_f32_e32 v178, v246, v246
	v_fmac_f32_e32 v178, v8, v8
	v_fmac_f32_e32 v178, v247, v247
	v_fmac_f32_e32 v178, v9, v9
	v_fmac_f32_e32 v178, v248, v248
	v_fmac_f32_e32 v178, v10, v10
	v_fmac_f32_e32 v178, v249, v249
	v_fmac_f32_e32 v178, v11, v11
	v_fmac_f32_e32 v178, v250, v250
	v_fmac_f32_e32 v178, v12, v12
	v_fmac_f32_e32 v178, v251, v251
	v_fmac_f32_e32 v178, v13, v13
	v_fmac_f32_e32 v178, v176, v176
	v_fmac_f32_e32 v178, v14, v14
	v_fmac_f32_e32 v178, v177, v177
	v_fmac_f32_e32 v178, v15, v15
	s_waitcnt vmcnt(16)
	v_lshlrev_b32_e32 v238, 16, v16
	v_and_b32_e32 v16, 0xffff0000, v16
	v_add_f32_dpp v178, v178, v178 quad_perm:[1,0,3,2] row_mask:0xf bank_mask:0xf bound_ctrl:1
	v_lshlrev_b32_e32 v239, 16, v17
	v_and_b32_e32 v17, 0xffff0000, v17
	v_add_f32_dpp v178, v178, v178 quad_perm:[2,3,0,1] row_mask:0xf bank_mask:0xf bound_ctrl:1
	v_lshlrev_b32_e32 v240, 16, v18
	v_and_b32_e32 v18, 0xffff0000, v18
	v_add_f32_dpp v178, v178, v178 row_half_mirror row_mask:0xf bank_mask:0xf bound_ctrl:1
	v_lshlrev_b32_e32 v241, 16, v19
	v_and_b32_e32 v19, 0xffff0000, v19
	v_add_f32_dpp v178, v178, v178 row_mirror row_mask:0xf bank_mask:0xf bound_ctrl:1
	v_lshlrev_b32_e32 v242, 16, v20
	v_and_b32_e32 v20, 0xffff0000, v20
	v_add_f32_dpp v178, v178, v178 row_bcast:15 row_mask:0xa bank_mask:0xf
	v_lshlrev_b32_e32 v243, 16, v21
	v_and_b32_e32 v21, 0xffff0000, v21
	v_add_f32_dpp v178, v178, v178 row_bcast:31 row_mask:0xc bank_mask:0xf
	v_lshlrev_b32_e32 v244, 16, v22
	v_and_b32_e32 v22, 0xffff0000, v22
	v_lshlrev_b32_e32 v245, 16, v23
	v_and_b32_e32 v23, 0xffff0000, v23
	v_readlane_b32 s0, v178, 63
	s_nop 1
	v_mov_b32_e32 v181, s0
	v_fmamk_f32 v181, v181, 0x3a800000, v161
	v_rsq_f32_e32 v179, v181
	s_nop 0
	v_mul_f32_e32 v246, v246, v179
	v_mul_f32_e32 v8, v8, v179
	v_mul_f32_e32 v247, v247, v179
	v_mul_f32_e32 v9, v9, v179
	v_mul_f32_e32 v248, v248, v179
	v_mul_f32_e32 v10, v10, v179
	v_mul_f32_e32 v249, v249, v179
	v_mul_f32_e32 v11, v11, v179
	v_mul_f32_e32 v250, v250, v179
	v_mul_f32_e32 v12, v12, v179
	v_mul_f32_e32 v251, v251, v179
	v_mul_f32_e32 v13, v13, v179
	v_mul_f32_e32 v176, v176, v179
	v_mul_f32_e32 v14, v14, v179
	v_mul_f32_e32 v177, v177, v179
	v_mul_f32_e32 v15, v15, v179
	v_mul_f32_e32 v246, v246, v56
	v_mul_f32_e32 v8, v8, v57
	v_mul_f32_e32 v247, v247, v58
	v_mul_f32_e32 v9, v9, v59
	v_mul_f32_e32 v248, v248, v60
	v_mul_f32_e32 v10, v10, v61
	v_mul_f32_e32 v249, v249, v62
	v_mul_f32_e32 v11, v11, v63
	v_mul_f32_e32 v250, v250, v64
	v_mul_f32_e32 v12, v12, v65
	v_mul_f32_e32 v251, v251, v66
	v_mul_f32_e32 v13, v13, v67
	v_mul_f32_e32 v176, v176, v68
	v_mul_f32_e32 v14, v14, v69
	v_mul_f32_e32 v177, v177, v70
	v_mul_f32_e32 v15, v15, v71
	v_fmac_f32_e32 v238, v88, v246
	v_fmac_f32_e32 v16, v89, v8
	v_fmac_f32_e32 v239, v90, v247
	v_fmac_f32_e32 v17, v91, v9
	v_fmac_f32_e32 v240, v92, v248
	v_fmac_f32_e32 v18, v93, v10
	v_fmac_f32_e32 v241, v94, v249
	v_fmac_f32_e32 v19, v95, v11
	v_fmac_f32_e32 v242, v96, v250
	v_fmac_f32_e32 v20, v97, v12
	v_fmac_f32_e32 v243, v98, v251
	v_fmac_f32_e32 v21, v99, v13
	v_fmac_f32_e32 v244, v100, v176
	v_fmac_f32_e32 v22, v101, v14
	v_fmac_f32_e32 v245, v102, v177
	v_fmac_f32_e32 v23, v103, v15
	v_add_u32_e32 v181, 0x1000000, v1
	v_mov_b32_e32 v120, v238
	v_mov_b32_e32 v121, v16
	v_mov_b32_e32 v122, v239
	v_mov_b32_e32 v123, v17
	global_store_dwordx4 v181, v[120:123], s[10:11] offset:0
	v_mov_b32_e32 v124, v240
	v_mov_b32_e32 v125, v18
	v_mov_b32_e32 v126, v241
	v_mov_b32_e32 v127, v19
	global_store_dwordx4 v181, v[124:127], s[10:11] offset:1024
	v_mov_b32_e32 v150, v242
	v_mov_b32_e32 v151, v20
	v_mov_b32_e32 v152, v243
	v_mov_b32_e32 v153, v21
	global_store_dwordx4 v181, v[150:153], s[10:11] offset:2048
	v_mov_b32_e32 v154, v244
	v_mov_b32_e32 v155, v22
	v_mov_b32_e32 v156, v245
	v_mov_b32_e32 v157, v23
	global_store_dwordx4 v181, v[154:157], s[10:11] offset:3072
	s_waitcnt vmcnt(16)
	v_lshlrev_b32_e32 v246, 16, v190
	v_and_b32_e32 v190, 0xffff0000, v190
	v_lshlrev_b32_e32 v247, 16, v191
	v_and_b32_e32 v191, 0xffff0000, v191
	v_lshlrev_b32_e32 v248, 16, v192
	v_and_b32_e32 v192, 0xffff0000, v192
	v_lshlrev_b32_e32 v249, 16, v193
	v_and_b32_e32 v193, 0xffff0000, v193
	v_lshlrev_b32_e32 v250, 16, v194
	v_and_b32_e32 v194, 0xffff0000, v194
	v_lshlrev_b32_e32 v251, 16, v195
	v_and_b32_e32 v195, 0xffff0000, v195
	v_lshlrev_b32_e32 v176, 16, v196
	v_and_b32_e32 v196, 0xffff0000, v196
	v_lshlrev_b32_e32 v177, 16, v197
	v_and_b32_e32 v197, 0xffff0000, v197
	v_mul_f32_e32 v178, v246, v246
	v_fmac_f32_e32 v178, v190, v190
	v_fmac_f32_e32 v178, v247, v247
	v_fmac_f32_e32 v178, v191, v191
	v_fmac_f32_e32 v178, v248, v248
	v_fmac_f32_e32 v178, v192, v192
	v_fmac_f32_e32 v178, v249, v249
	v_fmac_f32_e32 v178, v193, v193
	v_fmac_f32_e32 v178, v250, v250
	v_fmac_f32_e32 v178, v194, v194
	v_fmac_f32_e32 v178, v251, v251
	v_fmac_f32_e32 v178, v195, v195
	v_fmac_f32_e32 v178, v176, v176
	v_fmac_f32_e32 v178, v196, v196
	v_fmac_f32_e32 v178, v177, v177
	v_fmac_f32_e32 v178, v197, v197
	s_waitcnt vmcnt(12)
	v_lshlrev_b32_e32 v238, 16, v198
	v_and_b32_e32 v198, 0xffff0000, v198
	v_add_f32_dpp v178, v178, v178 quad_perm:[1,0,3,2] row_mask:0xf bank_mask:0xf bound_ctrl:1
	v_lshlrev_b32_e32 v239, 16, v199
	v_and_b32_e32 v199, 0xffff0000, v199
	v_add_f32_dpp v178, v178, v178 quad_perm:[2,3,0,1] row_mask:0xf bank_mask:0xf bound_ctrl:1
	v_lshlrev_b32_e32 v240, 16, v200
	v_and_b32_e32 v200, 0xffff0000, v200
	v_add_f32_dpp v178, v178, v178 row_half_mirror row_mask:0xf bank_mask:0xf bound_ctrl:1
	v_lshlrev_b32_e32 v241, 16, v201
	v_and_b32_e32 v201, 0xffff0000, v201
	v_add_f32_dpp v178, v178, v178 row_mirror row_mask:0xf bank_mask:0xf bound_ctrl:1
	v_lshlrev_b32_e32 v242, 16, v202
	v_and_b32_e32 v202, 0xffff0000, v202
	v_add_f32_dpp v178, v178, v178 row_bcast:15 row_mask:0xa bank_mask:0xf
	v_lshlrev_b32_e32 v243, 16, v203
	v_and_b32_e32 v203, 0xffff0000, v203
	v_add_f32_dpp v178, v178, v178 row_bcast:31 row_mask:0xc bank_mask:0xf
	v_lshlrev_b32_e32 v244, 16, v204
	v_and_b32_e32 v204, 0xffff0000, v204
	v_lshlrev_b32_e32 v245, 16, v205
	v_and_b32_e32 v205, 0xffff0000, v205
	v_readlane_b32 s0, v178, 63
	s_nop 1
	v_mov_b32_e32 v181, s0
	v_fmamk_f32 v181, v181, 0x3a800000, v161
	v_rsq_f32_e32 v179, v181
	s_nop 0
	v_mul_f32_e32 v246, v246, v179
	v_mul_f32_e32 v190, v190, v179
	v_mul_f32_e32 v247, v247, v179
	v_mul_f32_e32 v191, v191, v179
	v_mul_f32_e32 v248, v248, v179
	v_mul_f32_e32 v192, v192, v179
	v_mul_f32_e32 v249, v249, v179
	v_mul_f32_e32 v193, v193, v179
	v_mul_f32_e32 v250, v250, v179
	v_mul_f32_e32 v194, v194, v179
	v_mul_f32_e32 v251, v251, v179
	v_mul_f32_e32 v195, v195, v179
	v_mul_f32_e32 v176, v176, v179
	v_mul_f32_e32 v196, v196, v179
	v_mul_f32_e32 v177, v177, v179
	v_mul_f32_e32 v197, v197, v179
	v_mul_f32_e32 v246, v246, v56
	v_mul_f32_e32 v190, v190, v57
	v_mul_f32_e32 v247, v247, v58
	v_mul_f32_e32 v191, v191, v59
	v_mul_f32_e32 v248, v248, v60
	v_mul_f32_e32 v192, v192, v61
	v_mul_f32_e32 v249, v249, v62
	v_mul_f32_e32 v193, v193, v63
	v_mul_f32_e32 v250, v250, v64
	v_mul_f32_e32 v194, v194, v65
	v_mul_f32_e32 v251, v251, v66
	v_mul_f32_e32 v195, v195, v67
	v_mul_f32_e32 v176, v176, v68
	v_mul_f32_e32 v196, v196, v69
	v_mul_f32_e32 v177, v177, v70
	v_mul_f32_e32 v197, v197, v71
	v_fmac_f32_e32 v238, v88, v246
	v_fmac_f32_e32 v198, v89, v190
	v_fmac_f32_e32 v239, v90, v247
	v_fmac_f32_e32 v199, v91, v191
	v_fmac_f32_e32 v240, v92, v248
	v_fmac_f32_e32 v200, v93, v192
	v_fmac_f32_e32 v241, v94, v249
	v_fmac_f32_e32 v201, v95, v193
	v_fmac_f32_e32 v242, v96, v250
	v_fmac_f32_e32 v202, v97, v194
	v_fmac_f32_e32 v243, v98, v251
	v_fmac_f32_e32 v203, v99, v195
	v_fmac_f32_e32 v244, v100, v176
	v_fmac_f32_e32 v204, v101, v196
	v_fmac_f32_e32 v245, v102, v177
	v_fmac_f32_e32 v205, v103, v197
	v_add_u32_e32 v181, 0x1800000, v1
	v_mov_b32_e32 v120, v238
	v_mov_b32_e32 v121, v198
	v_mov_b32_e32 v122, v239
	v_mov_b32_e32 v123, v199
	global_store_dwordx4 v181, v[120:123], s[10:11] offset:0
	v_mov_b32_e32 v124, v240
	v_mov_b32_e32 v125, v200
	v_mov_b32_e32 v126, v241
	v_mov_b32_e32 v127, v201
	global_store_dwordx4 v181, v[124:127], s[10:11] offset:1024
	v_mov_b32_e32 v150, v242
	v_mov_b32_e32 v151, v202
	v_mov_b32_e32 v152, v243
	v_mov_b32_e32 v153, v203
	global_store_dwordx4 v181, v[150:153], s[10:11] offset:2048
	v_mov_b32_e32 v154, v244
	v_mov_b32_e32 v155, v204
	v_mov_b32_e32 v156, v245
	v_mov_b32_e32 v157, v205
	global_store_dwordx4 v181, v[154:157], s[10:11] offset:3072
	s_branch .LBB0_100

.LBB0_168:
	s_andn2_b64 vcc, exec, s[4:5]
	s_cbranch_vccnz .LBB0_213
	v_readlane_b32 s0, v254, 40
	s_cmp_gt_i32 s0, 4
	s_mov_b64 s[0:1], -1
	s_cbranch_scc0 .LBB0_190
	v_readfirstlane_b32 s0, v160
	v_readlane_b32 s1, v252, 7
	s_lshr_b32 s0, s0, 6
	s_mov_b32 s73, s0
	s_add_i32 s0, s0, s1
	v_readlane_b32 s62, v254, 34
	s_sub_u32 s64, s78, 0x110
	s_subb_u32 s65, s79, 0
	s_load_dwordx2 s[66:67], s[64:65], 0x40
	s_load_dwordx2 s[10:11], s[64:65], 0xf8
	s_lshl_b32 s63, s0, 11
	s_add_u32 s4, s84, 0x167ca000
	s_addc_u32 s5, s85, 0
	s_add_u32 s4, s4, s63
	s_addc_u32 s5, s5, 0
	s_add_u32 s6, s84, 0x112ca000
	s_addc_u32 s7, s85, 0
	s_add_u32 s6, s6, s63
	s_addc_u32 s7, s7, 0
	v_and_b32_e32 v0, 63, v160
	v_lshlrev_b32_e32 v1, 4, v0
	v_lshlrev_b32_e32 v0, 3, v0
	v_add_u32_e32 v2, 0x400000, v0
	v_add_u32_e32 v3, 0x800000, v0
	v_add_u32_e32 v4, 0xc00000, v0
	v_add_u32_e32 v5, 0x1000000, v0
	global_load_dwordx2 v[8:9], v5, s[6:7] offset:0 nt
	global_load_dwordx2 v[10:11], v5, s[6:7] offset:512 nt
	global_load_dwordx2 v[12:13], v5, s[6:7] offset:1024 nt
	global_load_dwordx2 v[14:15], v5, s[6:7] offset:1536 nt
	global_load_dwordx2 v[16:17], v5, s[4:5] offset:0 nt
	global_load_dwordx2 v[18:19], v5, s[4:5] offset:512 nt
	global_load_dwordx2 v[20:21], v5, s[4:5] offset:1024 nt
	global_load_dwordx2 v[22:23], v5, s[4:5] offset:1536 nt
	s_add_u32 s8, s84, 0xaeca000
	s_addc_u32 s9, s85, 0
	s_add_u32 s8, s8, s63
	s_addc_u32 s9, s9, 0
	s_lshr_b32 s69, s0, 10
	s_add_i32 s69, s69, 1
	s_mul_i32 s69, s69, 0x6000
	s_mul_i32 s68, s62, 0x12000
	s_lshl_b32 s72, s62, 14
	s_add_i32 s70, s72, 0x2000
	s_add_i32 s72, s72, 0x1000
	s_add_u32 s16, s84, 0x6602000
	s_addc_u32 s17, s85, 0
	s_add_u32 s16, s16, s68
	s_addc_u32 s17, s17, 0
	s_add_u32 s20, s16, 0x1000
	s_addc_u32 s21, s17, 0
	s_add_u32 s18, s16, 0x2000
	s_addc_u32 s19, s17, 0
	s_add_u32 s22, s16, s69
	s_addc_u32 s23, s17, 0
	s_add_u32 s60, s20, s69
	s_addc_u32 s61, s21, 0
	s_add_u32 s26, s18, s69
	s_addc_u32 s27, s19, 0
	s_lshl_b32 s63, s63, 1
	s_waitcnt lgkmcnt(0)
	s_add_u32 s12, s66, s72
	s_addc_u32 s13, s67, 0
	s_add_u32 s14, s66, s70
	s_addc_u32 s15, s67, 0
	s_add_u32 s10, s10, s63
	s_addc_u32 s11, s11, 0
	s_mov_b64 s[74:75], s[12:13]
	s_cmp_eq_u32 s73, 1
	s_cselect_b32 s74, s14, s74
	s_cselect_b32 s75, s15, s75
	s_cmp_eq_u32 s73, 2
	s_cselect_b32 s74, s16, s74
	s_cselect_b32 s75, s17, s75
	s_cmp_eq_u32 s73, 3
	s_cselect_b32 s74, s18, s74
	s_cselect_b32 s75, s19, s75
	s_cmp_eq_u32 s73, 4
	s_cselect_b32 s74, s20, s74
	s_cselect_b32 s75, s21, s75
	s_cmp_eq_u32 s73, 5
	s_cselect_b32 s74, s22, s74
	s_cselect_b32 s75, s23, s75
	s_cmp_eq_u32 s73, 6
	s_cselect_b32 s74, s26, s74
	s_cselect_b32 s75, s27, s75
	s_cmp_eq_u32 s73, 7
	s_cselect_b32 s74, s60, s74
	s_cselect_b32 s75, s61, s75
	global_load_dwordx4 v[222:225], v1, s[74:75] offset:0
	global_load_dwordx4 v[226:229], v1, s[74:75] offset:1024
	global_load_dwordx4 v[230:233], v1, s[74:75] offset:2048
	global_load_dwordx4 v[234:237], v1, s[74:75] offset:3072
	s_lshl_b32 s74, s73, 12
	v_add_u32_e32 v6, s74, v1
	global_load_dwordx2 v[24:25], v0, s[6:7] offset:0 nt
	global_load_dwordx2 v[26:27], v0, s[6:7] offset:512 nt
	global_load_dwordx2 v[28:29], v0, s[6:7] offset:1024 nt
	global_load_dwordx2 v[30:31], v0, s[6:7] offset:1536 nt
	global_load_dwordx2 v[32:33], v0, s[4:5] offset:0 nt
	global_load_dwordx2 v[34:35], v0, s[4:5] offset:512 nt
	global_load_dwordx2 v[36:37], v0, s[4:5] offset:1024 nt
	global_load_dwordx2 v[38:39], v0, s[4:5] offset:1536 nt
	global_load_dwordx2 v[40:41], v2, s[6:7] offset:0 nt
	global_load_dwordx2 v[42:43], v2, s[6:7] offset:512 nt
	global_load_dwordx2 v[44:45], v2, s[6:7] offset:1024 nt
	global_load_dwordx2 v[46:47], v2, s[6:7] offset:1536 nt
	global_load_dwordx2 v[48:49], v2, s[4:5] offset:0 nt
	global_load_dwordx2 v[50:51], v2, s[4:5] offset:512 nt
	global_load_dwordx2 v[52:53], v2, s[4:5] offset:1024 nt
	global_load_dwordx2 v[54:55], v2, s[4:5] offset:1536 nt
	s_waitcnt vmcnt(16)
	ds_write_b128 v6, v[222:225] offset:0
	ds_write_b128 v6, v[226:229] offset:1024
	ds_write_b128 v6, v[230:233] offset:2048
	ds_write_b128 v6, v[234:237] offset:3072
	s_waitcnt lgkmcnt(0)
	s_barrier
	ds_read_b128 v[56:59], v1 offset:0
	ds_read_b128 v[60:63], v1 offset:1024
	ds_read_b128 v[64:67], v1 offset:2048
	ds_read_b128 v[68:71], v1 offset:3072
	ds_read_b128 v[72:75], v1 offset:4096
	ds_read_b128 v[76:79], v1 offset:5120
	ds_read_b128 v[80:83], v1 offset:6144
	ds_read_b128 v[84:87], v1 offset:7168
	ds_read_b128 v[88:91], v1 offset:8192
	ds_read_b128 v[92:95], v1 offset:9216
	ds_read_b128 v[96:99], v1 offset:10240
	ds_read_b128 v[100:103], v1 offset:11264
	ds_read_b128 v[104:107], v1 offset:12288
	ds_read_b128 v[108:111], v1 offset:13312
	ds_read_b128 v[112:115], v1 offset:14336
	ds_read_b128 v[116:119], v1 offset:15360
	ds_read_b128 v[134:137], v1 offset:16384
	ds_read_b128 v[138:141], v1 offset:17408
	ds_read_b128 v[142:145], v1 offset:18432
	ds_read_b128 v[146:149], v1 offset:19456
	ds_read_b128 v[190:193], v1 offset:20480
	ds_read_b128 v[194:197], v1 offset:21504
	ds_read_b128 v[198:201], v1 offset:22528
	ds_read_b128 v[202:205], v1 offset:23552
	ds_read_b128 v[206:209], v1 offset:24576
	ds_read_b128 v[210:213], v1 offset:25600
	ds_read_b128 v[214:217], v1 offset:26624
	ds_read_b128 v[218:221], v1 offset:27648
	ds_read_b128 v[222:225], v1 offset:28672
	ds_read_b128 v[226:229], v1 offset:29696
	ds_read_b128 v[230:233], v1 offset:30720
	ds_read_b128 v[234:237], v1 offset:31744
	v_lshlrev_b32_e32 v246, 16, v8
	v_and_b32_e32 v8, 0xffff0000, v8
	v_lshlrev_b32_e32 v247, 16, v9
	v_and_b32_e32 v9, 0xffff0000, v9
	v_lshlrev_b32_e32 v248, 16, v10
	v_and_b32_e32 v10, 0xffff0000, v10
	v_lshlrev_b32_e32 v249, 16, v11
	v_and_b32_e32 v11, 0xffff0000, v11
	v_lshlrev_b32_e32 v250, 16, v12
	v_and_b32_e32 v12, 0xffff0000, v12
	v_lshlrev_b32_e32 v251, 16, v13
	v_and_b32_e32 v13, 0xffff0000, v13
	v_lshlrev_b32_e32 v176, 16, v14
	v_and_b32_e32 v14, 0xffff0000, v14
	v_lshlrev_b32_e32 v177, 16, v15
	v_and_b32_e32 v15, 0xffff0000, v15
	v_mul_f32_e32 v178, v246, v246
	v_fmac_f32_e32 v178, v8, v8
	v_fmac_f32_e32 v178, v247, v247
	v_fmac_f32_e32 v178, v9, v9
	v_fmac_f32_e32 v178, v248, v248
	v_fmac_f32_e32 v178, v10, v10
	v_fmac_f32_e32 v178, v249, v249
	v_fmac_f32_e32 v178, v11, v11
	v_fmac_f32_e32 v178, v250, v250
	v_fmac_f32_e32 v178, v12, v12
	v_fmac_f32_e32 v178, v251, v251
	v_fmac_f32_e32 v178, v13, v13
	v_fmac_f32_e32 v178, v176, v176
	v_fmac_f32_e32 v178, v14, v14
	v_fmac_f32_e32 v178, v177, v177
	v_fmac_f32_e32 v178, v15, v15
	v_lshlrev_b32_e32 v238, 16, v16
	v_and_b32_e32 v16, 0xffff0000, v16
	v_add_f32_dpp v178, v178, v178 quad_perm:[1,0,3,2] row_mask:0xf bank_mask:0xf bound_ctrl:1
	v_lshlrev_b32_e32 v239, 16, v17
	v_and_b32_e32 v17, 0xffff0000, v17
	v_add_f32_dpp v178, v178, v178 quad_perm:[2,3,0,1] row_mask:0xf bank_mask:0xf bound_ctrl:1
	v_lshlrev_b32_e32 v240, 16, v18
	v_and_b32_e32 v18, 0xffff0000, v18
	v_add_f32_dpp v178, v178, v178 row_half_mirror row_mask:0xf bank_mask:0xf bound_ctrl:1
	v_lshlrev_b32_e32 v241, 16, v19
	v_and_b32_e32 v19, 0xffff0000, v19
	v_add_f32_dpp v178, v178, v178 row_mirror row_mask:0xf bank_mask:0xf bound_ctrl:1
	v_lshlrev_b32_e32 v242, 16, v20
	v_and_b32_e32 v20, 0xffff0000, v20
	v_add_f32_dpp v178, v178, v178 row_bcast:15 row_mask:0xa bank_mask:0xf
	v_lshlrev_b32_e32 v243, 16, v21
	v_and_b32_e32 v21, 0xffff0000, v21
	v_add_f32_dpp v178, v178, v178 row_bcast:31 row_mask:0xc bank_mask:0xf
	v_lshlrev_b32_e32 v244, 16, v22
	v_and_b32_e32 v22, 0xffff0000, v22
	v_lshlrev_b32_e32 v245, 16, v23
	v_and_b32_e32 v23, 0xffff0000, v23
	v_readlane_b32 s0, v178, 63
	s_nop 1
	v_mov_b32_e32 v181, s0
	v_fmamk_f32 v181, v181, 0x3a800000, v161
	v_rsq_f32_e32 v179, v181
	s_nop 0
	s_waitcnt lgkmcnt(0)
	v_mul_f32_e32 v246, v246, v179
	v_mul_f32_e32 v8, v8, v179
	v_mul_f32_e32 v247, v247, v179
	v_mul_f32_e32 v9, v9, v179
	v_mul_f32_e32 v248, v248, v179
	v_mul_f32_e32 v10, v10, v179
	v_mul_f32_e32 v249, v249, v179
	v_mul_f32_e32 v11, v11, v179
	v_mul_f32_e32 v250, v250, v179
	v_mul_f32_e32 v12, v12, v179
	v_mul_f32_e32 v251, v251, v179
	v_mul_f32_e32 v13, v13, v179
	v_mul_f32_e32 v176, v176, v179
	v_mul_f32_e32 v14, v14, v179
	v_mul_f32_e32 v177, v177, v179
	v_mul_f32_e32 v15, v15, v179
	v_mul_f32_e32 v246, v246, v56
	v_mul_f32_e32 v8, v8, v57
	v_mul_f32_e32 v247, v247, v58
	v_mul_f32_e32 v9, v9, v59
	v_mul_f32_e32 v248, v248, v60
	v_mul_f32_e32 v10, v10, v61
	v_mul_f32_e32 v249, v249, v62
	v_mul_f32_e32 v11, v11, v63
	v_mul_f32_e32 v250, v250, v64
	v_mul_f32_e32 v12, v12, v65
	v_mul_f32_e32 v251, v251, v66
	v_mul_f32_e32 v13, v13, v67
	v_mul_f32_e32 v176, v176, v68
	v_mul_f32_e32 v14, v14, v69
	v_mul_f32_e32 v177, v177, v70
	v_mul_f32_e32 v15, v15, v71
	v_fmac_f32_e32 v238, v190, v246
	v_fmac_f32_e32 v16, v191, v8
	v_fmac_f32_e32 v239, v192, v247
	v_fmac_f32_e32 v17, v193, v9
	v_fmac_f32_e32 v240, v194, v248
	v_fmac_f32_e32 v18, v195, v10
	v_fmac_f32_e32 v241, v196, v249
	v_fmac_f32_e32 v19, v197, v11
	v_fmac_f32_e32 v242, v198, v250
	v_fmac_f32_e32 v20, v199, v12
	v_fmac_f32_e32 v243, v200, v251
	v_fmac_f32_e32 v21, v201, v13
	v_fmac_f32_e32 v244, v202, v176
	v_fmac_f32_e32 v22, v203, v14
	v_fmac_f32_e32 v245, v204, v177
	v_fmac_f32_e32 v23, v205, v15
	v_cvt_pk_bf16_f32 v120, v238, v16
	v_cvt_pk_bf16_f32 v121, v239, v17
	global_store_dwordx2 v5, v[120:121], s[4:5] offset:0 nt
	v_cvt_pk_bf16_f32 v122, v240, v18
	v_cvt_pk_bf16_f32 v123, v241, v19
	global_store_dwordx2 v5, v[122:123], s[4:5] offset:512 nt
	v_cvt_pk_bf16_f32 v124, v242, v20
	v_cvt_pk_bf16_f32 v125, v243, v21
	global_store_dwordx2 v5, v[124:125], s[4:5] offset:1024 nt
	v_cvt_pk_bf16_f32 v126, v244, v22
	v_cvt_pk_bf16_f32 v127, v245, v23
	global_store_dwordx2 v5, v[126:127], s[4:5] offset:1536 nt
	v_mul_f32_e32 v178, v238, v238
	v_fmac_f32_e32 v178, v16, v16
	v_fmac_f32_e32 v178, v239, v239
	v_fmac_f32_e32 v178, v17, v17
	v_fmac_f32_e32 v178, v240, v240
	v_fmac_f32_e32 v178, v18, v18
	v_fmac_f32_e32 v178, v241, v241
	v_fmac_f32_e32 v178, v19, v19
	v_fmac_f32_e32 v178, v242, v242
	v_fmac_f32_e32 v178, v20, v20
	v_fmac_f32_e32 v178, v243, v243
	v_fmac_f32_e32 v178, v21, v21
	v_fmac_f32_e32 v178, v244, v244
	v_fmac_f32_e32 v178, v22, v22
	v_fmac_f32_e32 v178, v245, v245
	v_fmac_f32_e32 v178, v23, v23
	v_add_f32_e32 v206, 1.0, v206
	v_add_f32_e32 v207, 1.0, v207
	v_add_f32_dpp v178, v178, v178 quad_perm:[1,0,3,2] row_mask:0xf bank_mask:0xf bound_ctrl:1
	v_add_f32_e32 v208, 1.0, v208
	v_add_f32_e32 v209, 1.0, v209
	v_add_f32_dpp v178, v178, v178 quad_perm:[2,3,0,1] row_mask:0xf bank_mask:0xf bound_ctrl:1
	v_add_f32_e32 v210, 1.0, v210
	v_add_f32_e32 v211, 1.0, v211
	v_add_f32_dpp v178, v178, v178 row_half_mirror row_mask:0xf bank_mask:0xf bound_ctrl:1
	v_add_f32_e32 v212, 1.0, v212
	v_add_f32_e32 v213, 1.0, v213
	v_add_f32_dpp v178, v178, v178 row_mirror row_mask:0xf bank_mask:0xf bound_ctrl:1
	v_add_f32_e32 v214, 1.0, v214
	v_add_f32_e32 v215, 1.0, v215
	v_add_f32_dpp v178, v178, v178 row_bcast:15 row_mask:0xa bank_mask:0xf
	v_add_f32_e32 v216, 1.0, v216
	v_add_f32_e32 v217, 1.0, v217
	v_add_f32_dpp v178, v178, v178 row_bcast:31 row_mask:0xc bank_mask:0xf
	v_add_f32_e32 v218, 1.0, v218
	v_add_f32_e32 v219, 1.0, v219
	v_add_f32_e32 v220, 1.0, v220
	v_add_f32_e32 v221, 1.0, v221
	v_readlane_b32 s0, v178, 63
	s_nop 1
	v_mov_b32_e32 v181, s0
	v_fmamk_f32 v181, v181, 0x3a800000, v161
	v_rsq_f32_e32 v180, v181
	s_nop 0
	v_mul_f32_e32 v238, v238, v180
	v_mul_f32_e32 v16, v16, v180
	v_mul_f32_e32 v239, v239, v180
	v_mul_f32_e32 v17, v17, v180
	v_mul_f32_e32 v240, v240, v180
	v_mul_f32_e32 v18, v18, v180
	v_mul_f32_e32 v241, v241, v180
	v_mul_f32_e32 v19, v19, v180
	v_mul_f32_e32 v242, v242, v180
	v_mul_f32_e32 v20, v20, v180
	v_mul_f32_e32 v243, v243, v180
	v_mul_f32_e32 v21, v21, v180
	v_mul_f32_e32 v244, v244, v180
	v_mul_f32_e32 v22, v22, v180
	v_mul_f32_e32 v245, v245, v180
	v_mul_f32_e32 v23, v23, v180
	v_mul_f32_e32 v238, v238, v72
	v_mul_f32_e32 v16, v16, v73
	v_mul_f32_e32 v239, v239, v74
	v_mul_f32_e32 v17, v17, v75
	v_mul_f32_e32 v240, v240, v76
	v_mul_f32_e32 v18, v18, v77
	v_mul_f32_e32 v241, v241, v78
	v_mul_f32_e32 v19, v19, v79
	v_mul_f32_e32 v242, v242, v80
	v_mul_f32_e32 v20, v20, v81
	v_mul_f32_e32 v243, v243, v82
	v_mul_f32_e32 v21, v21, v83
	v_mul_f32_e32 v244, v244, v84
	v_mul_f32_e32 v22, v22, v85
	v_mul_f32_e32 v245, v245, v86
	v_mul_f32_e32 v23, v23, v87
	v_fma_f32 v238, v238, v206, v222
	v_fma_f32 v16, v16, v207, v223
	v_fma_f32 v239, v239, v208, v224
	v_fma_f32 v17, v17, v209, v225
	v_fma_f32 v240, v240, v210, v226
	v_fma_f32 v18, v18, v211, v227
	v_fma_f32 v241, v241, v212, v228
	v_fma_f32 v19, v19, v213, v229
	v_fma_f32 v242, v242, v214, v230
	v_fma_f32 v20, v20, v215, v231
	v_fma_f32 v243, v243, v216, v232
	v_fma_f32 v21, v21, v217, v233
	v_fma_f32 v244, v244, v218, v234
	v_fma_f32 v22, v22, v219, v235
	v_fma_f32 v245, v245, v220, v236
	v_fma_f32 v23, v23, v221, v237
	v_cvt_pk_bf16_f32 v150, v238, v16
	v_cvt_pk_bf16_f32 v151, v239, v17
	global_store_dwordx2 v5, v[150:151], s[8:9] offset:0
	v_cvt_pk_bf16_f32 v152, v240, v18
	v_cvt_pk_bf16_f32 v153, v241, v19
	global_store_dwordx2 v5, v[152:153], s[8:9] offset:512
	v_cvt_pk_bf16_f32 v154, v242, v20
	v_cvt_pk_bf16_f32 v155, v243, v21
	global_store_dwordx2 v5, v[154:155], s[8:9] offset:1024
	v_cvt_pk_bf16_f32 v156, v244, v22
	v_cvt_pk_bf16_f32 v157, v245, v23
	global_store_dwordx2 v5, v[156:157], s[8:9] offset:1536
	global_load_dwordx2 v[8:9], v3, s[6:7] offset:0 nt
	global_load_dwordx2 v[10:11], v3, s[6:7] offset:512 nt
	global_load_dwordx2 v[12:13], v3, s[6:7] offset:1024 nt
	global_load_dwordx2 v[14:15], v3, s[6:7] offset:1536 nt
	global_load_dwordx2 v[16:17], v3, s[4:5] offset:0 nt
	global_load_dwordx2 v[18:19], v3, s[4:5] offset:512 nt
	global_load_dwordx2 v[20:21], v3, s[4:5] offset:1024 nt
	global_load_dwordx2 v[22:23], v3, s[4:5] offset:1536 nt
	global_load_dwordx2 v[190:191], v4, s[6:7] offset:0 nt
	global_load_dwordx2 v[192:193], v4, s[6:7] offset:512 nt
	global_load_dwordx2 v[194:195], v4, s[6:7] offset:1024 nt
	global_load_dwordx2 v[196:197], v4, s[6:7] offset:1536 nt
	global_load_dwordx2 v[198:199], v4, s[4:5] offset:0 nt
	global_load_dwordx2 v[200:201], v4, s[4:5] offset:512 nt
	global_load_dwordx2 v[202:203], v4, s[4:5] offset:1024 nt
	global_load_dwordx2 v[204:205], v4, s[4:5] offset:1536 nt
	s_waitcnt vmcnt(36)
	v_lshlrev_b32_e32 v246, 16, v24
	v_and_b32_e32 v24, 0xffff0000, v24
	v_lshlrev_b32_e32 v247, 16, v25
	v_and_b32_e32 v25, 0xffff0000, v25
	v_lshlrev_b32_e32 v248, 16, v26
	v_and_b32_e32 v26, 0xffff0000, v26
	v_lshlrev_b32_e32 v249, 16, v27
	v_and_b32_e32 v27, 0xffff0000, v27
	v_lshlrev_b32_e32 v250, 16, v28
	v_and_b32_e32 v28, 0xffff0000, v28
	v_lshlrev_b32_e32 v251, 16, v29
	v_and_b32_e32 v29, 0xffff0000, v29
	v_lshlrev_b32_e32 v176, 16, v30
	v_and_b32_e32 v30, 0xffff0000, v30
	v_lshlrev_b32_e32 v177, 16, v31
	v_and_b32_e32 v31, 0xffff0000, v31
	v_mul_f32_e32 v178, v246, v246
	v_fmac_f32_e32 v178, v24, v24
	v_fmac_f32_e32 v178, v247, v247
	v_fmac_f32_e32 v178, v25, v25
	v_fmac_f32_e32 v178, v248, v248
	v_fmac_f32_e32 v178, v26, v26
	v_fmac_f32_e32 v178, v249, v249
	v_fmac_f32_e32 v178, v27, v27
	v_fmac_f32_e32 v178, v250, v250
	v_fmac_f32_e32 v178, v28, v28
	v_fmac_f32_e32 v178, v251, v251
	v_fmac_f32_e32 v178, v29, v29
	v_fmac_f32_e32 v178, v176, v176
	v_fmac_f32_e32 v178, v30, v30
	v_fmac_f32_e32 v178, v177, v177
	v_fmac_f32_e32 v178, v31, v31
	s_waitcnt vmcnt(32)
	v_lshlrev_b32_e32 v238, 16, v32
	v_and_b32_e32 v32, 0xffff0000, v32
	v_add_f32_dpp v178, v178, v178 quad_perm:[1,0,3,2] row_mask:0xf bank_mask:0xf bound_ctrl:1
	v_lshlrev_b32_e32 v239, 16, v33
	v_and_b32_e32 v33, 0xffff0000, v33
	v_add_f32_dpp v178, v178, v178 quad_perm:[2,3,0,1] row_mask:0xf bank_mask:0xf bound_ctrl:1
	v_lshlrev_b32_e32 v240, 16, v34
	v_and_b32_e32 v34, 0xffff0000, v34
	v_add_f32_dpp v178, v178, v178 row_half_mirror row_mask:0xf bank_mask:0xf bound_ctrl:1
	v_lshlrev_b32_e32 v241, 16, v35
	v_and_b32_e32 v35, 0xffff0000, v35
	v_add_f32_dpp v178, v178, v178 row_mirror row_mask:0xf bank_mask:0xf bound_ctrl:1
	v_lshlrev_b32_e32 v242, 16, v36
	v_and_b32_e32 v36, 0xffff0000, v36
	v_add_f32_dpp v178, v178, v178 row_bcast:15 row_mask:0xa bank_mask:0xf
	v_lshlrev_b32_e32 v243, 16, v37
	v_and_b32_e32 v37, 0xffff0000, v37
	v_add_f32_dpp v178, v178, v178 row_bcast:31 row_mask:0xc bank_mask:0xf
	v_lshlrev_b32_e32 v244, 16, v38
	v_and_b32_e32 v38, 0xffff0000, v38
	v_lshlrev_b32_e32 v245, 16, v39
	v_and_b32_e32 v39, 0xffff0000, v39
	v_readlane_b32 s0, v178, 63
	s_nop 1
	v_mov_b32_e32 v181, s0
	v_fmamk_f32 v181, v181, 0x3a800000, v161
	v_rsq_f32_e32 v179, v181
	s_nop 0
	v_mul_f32_e32 v246, v246, v179
	v_mul_f32_e32 v24, v24, v179
	v_mul_f32_e32 v247, v247, v179
	v_mul_f32_e32 v25, v25, v179
	v_mul_f32_e32 v248, v248, v179
	v_mul_f32_e32 v26, v26, v179
	v_mul_f32_e32 v249, v249, v179
	v_mul_f32_e32 v27, v27, v179
	v_mul_f32_e32 v250, v250, v179
	v_mul_f32_e32 v28, v28, v179
	v_mul_f32_e32 v251, v251, v179
	v_mul_f32_e32 v29, v29, v179
	v_mul_f32_e32 v176, v176, v179
	v_mul_f32_e32 v30, v30, v179
	v_mul_f32_e32 v177, v177, v179
	v_mul_f32_e32 v31, v31, v179
	v_mul_f32_e32 v246, v246, v56
	v_mul_f32_e32 v24, v24, v57
	v_mul_f32_e32 v247, v247, v58
	v_mul_f32_e32 v25, v25, v59
	v_mul_f32_e32 v248, v248, v60
	v_mul_f32_e32 v26, v26, v61
	v_mul_f32_e32 v249, v249, v62
	v_mul_f32_e32 v27, v27, v63
	v_mul_f32_e32 v250, v250, v64
	v_mul_f32_e32 v28, v28, v65
	v_mul_f32_e32 v251, v251, v66
	v_mul_f32_e32 v29, v29, v67
	v_mul_f32_e32 v176, v176, v68
	v_mul_f32_e32 v30, v30, v69
	v_mul_f32_e32 v177, v177, v70
	v_mul_f32_e32 v31, v31, v71
	v_fmac_f32_e32 v238, v88, v246
	v_fmac_f32_e32 v32, v89, v24
	v_fmac_f32_e32 v239, v90, v247
	v_fmac_f32_e32 v33, v91, v25
	v_fmac_f32_e32 v240, v92, v248
	v_fmac_f32_e32 v34, v93, v26
	v_fmac_f32_e32 v241, v94, v249
	v_fmac_f32_e32 v35, v95, v27
	v_fmac_f32_e32 v242, v96, v250
	v_fmac_f32_e32 v36, v97, v28
	v_fmac_f32_e32 v243, v98, v251
	v_fmac_f32_e32 v37, v99, v29
	v_fmac_f32_e32 v244, v100, v176
	v_fmac_f32_e32 v38, v101, v30
	v_fmac_f32_e32 v245, v102, v177
	v_fmac_f32_e32 v39, v103, v31
	v_cvt_pk_bf16_f32 v120, v238, v32
	v_cvt_pk_bf16_f32 v121, v239, v33
	global_store_dwordx2 v0, v[120:121], s[4:5] offset:0 nt
	v_cvt_pk_bf16_f32 v122, v240, v34
	v_cvt_pk_bf16_f32 v123, v241, v35
	global_store_dwordx2 v0, v[122:123], s[4:5] offset:512 nt
	v_cvt_pk_bf16_f32 v124, v242, v36
	v_cvt_pk_bf16_f32 v125, v243, v37
	global_store_dwordx2 v0, v[124:125], s[4:5] offset:1024 nt
	v_cvt_pk_bf16_f32 v126, v244, v38
	v_cvt_pk_bf16_f32 v127, v245, v39
	global_store_dwordx2 v0, v[126:127], s[4:5] offset:1536 nt
	v_mul_f32_e32 v178, v238, v238
	v_fmac_f32_e32 v178, v32, v32
	v_fmac_f32_e32 v178, v239, v239
	v_fmac_f32_e32 v178, v33, v33
	v_fmac_f32_e32 v178, v240, v240
	v_fmac_f32_e32 v178, v34, v34
	v_fmac_f32_e32 v178, v241, v241
	v_fmac_f32_e32 v178, v35, v35
	v_fmac_f32_e32 v178, v242, v242
	v_fmac_f32_e32 v178, v36, v36
	v_fmac_f32_e32 v178, v243, v243
	v_fmac_f32_e32 v178, v37, v37
	v_fmac_f32_e32 v178, v244, v244
	v_fmac_f32_e32 v178, v38, v38
	v_fmac_f32_e32 v178, v245, v245
	v_fmac_f32_e32 v178, v39, v39
	v_add_f32_e32 v104, 1.0, v104
	v_add_f32_e32 v105, 1.0, v105
	v_add_f32_dpp v178, v178, v178 quad_perm:[1,0,3,2] row_mask:0xf bank_mask:0xf bound_ctrl:1
	v_add_f32_e32 v106, 1.0, v106
	v_add_f32_e32 v107, 1.0, v107
	v_add_f32_dpp v178, v178, v178 quad_perm:[2,3,0,1] row_mask:0xf bank_mask:0xf bound_ctrl:1
	v_add_f32_e32 v108, 1.0, v108
	v_add_f32_e32 v109, 1.0, v109
	v_add_f32_dpp v178, v178, v178 row_half_mirror row_mask:0xf bank_mask:0xf bound_ctrl:1
	v_add_f32_e32 v110, 1.0, v110
	v_add_f32_e32 v111, 1.0, v111
	v_add_f32_dpp v178, v178, v178 row_mirror row_mask:0xf bank_mask:0xf bound_ctrl:1
	v_add_f32_e32 v112, 1.0, v112
	v_add_f32_e32 v113, 1.0, v113
	v_add_f32_dpp v178, v178, v178 row_bcast:15 row_mask:0xa bank_mask:0xf
	v_add_f32_e32 v114, 1.0, v114
	v_add_f32_e32 v115, 1.0, v115
	v_add_f32_dpp v178, v178, v178 row_bcast:31 row_mask:0xc bank_mask:0xf
	v_add_f32_e32 v116, 1.0, v116
	v_add_f32_e32 v117, 1.0, v117
	v_add_f32_e32 v118, 1.0, v118
	v_add_f32_e32 v119, 1.0, v119
	v_readlane_b32 s0, v178, 63
	s_nop 1
	v_mov_b32_e32 v181, s0
	v_fmamk_f32 v181, v181, 0x3a800000, v161
	v_rsq_f32_e32 v180, v181
	s_nop 0
	v_mul_f32_e32 v238, v238, v180
	v_mul_f32_e32 v32, v32, v180
	v_mul_f32_e32 v239, v239, v180
	v_mul_f32_e32 v33, v33, v180
	v_mul_f32_e32 v240, v240, v180
	v_mul_f32_e32 v34, v34, v180
	v_mul_f32_e32 v241, v241, v180
	v_mul_f32_e32 v35, v35, v180
	v_mul_f32_e32 v242, v242, v180
	v_mul_f32_e32 v36, v36, v180
	v_mul_f32_e32 v243, v243, v180
	v_mul_f32_e32 v37, v37, v180
	v_mul_f32_e32 v244, v244, v180
	v_mul_f32_e32 v38, v38, v180
	v_mul_f32_e32 v245, v245, v180
	v_mul_f32_e32 v39, v39, v180
	v_mul_f32_e32 v238, v238, v72
	v_mul_f32_e32 v32, v32, v73
	v_mul_f32_e32 v239, v239, v74
	v_mul_f32_e32 v33, v33, v75
	v_mul_f32_e32 v240, v240, v76
	v_mul_f32_e32 v34, v34, v77
	v_mul_f32_e32 v241, v241, v78
	v_mul_f32_e32 v35, v35, v79
	v_mul_f32_e32 v242, v242, v80
	v_mul_f32_e32 v36, v36, v81
	v_mul_f32_e32 v243, v243, v82
	v_mul_f32_e32 v37, v37, v83
	v_mul_f32_e32 v244, v244, v84
	v_mul_f32_e32 v38, v38, v85
	v_mul_f32_e32 v245, v245, v86
	v_mul_f32_e32 v39, v39, v87
	v_fma_f32 v238, v238, v104, v134
	v_fma_f32 v32, v32, v105, v135
	v_fma_f32 v239, v239, v106, v136
	v_fma_f32 v33, v33, v107, v137
	v_fma_f32 v240, v240, v108, v138
	v_fma_f32 v34, v34, v109, v139
	v_fma_f32 v241, v241, v110, v140
	v_fma_f32 v35, v35, v111, v141
	v_fma_f32 v242, v242, v112, v142
	v_fma_f32 v36, v36, v113, v143
	v_fma_f32 v243, v243, v114, v144
	v_fma_f32 v37, v37, v115, v145
	v_fma_f32 v244, v244, v116, v146
	v_fma_f32 v38, v38, v117, v147
	v_fma_f32 v245, v245, v118, v148
	v_fma_f32 v39, v39, v119, v149
	v_cvt_pk_bf16_f32 v150, v238, v32
	v_cvt_pk_bf16_f32 v151, v239, v33
	global_store_dwordx2 v0, v[150:151], s[8:9] offset:0
	v_cvt_pk_bf16_f32 v152, v240, v34
	v_cvt_pk_bf16_f32 v153, v241, v35
	global_store_dwordx2 v0, v[152:153], s[8:9] offset:512
	v_cvt_pk_bf16_f32 v154, v242, v36
	v_cvt_pk_bf16_f32 v155, v243, v37
	global_store_dwordx2 v0, v[154:155], s[8:9] offset:1024
	v_cvt_pk_bf16_f32 v156, v244, v38
	v_cvt_pk_bf16_f32 v157, v245, v39
	global_store_dwordx2 v0, v[156:157], s[8:9] offset:1536
	s_waitcnt vmcnt(36)
	v_lshlrev_b32_e32 v246, 16, v40
	v_and_b32_e32 v40, 0xffff0000, v40
	v_lshlrev_b32_e32 v247, 16, v41
	v_and_b32_e32 v41, 0xffff0000, v41
	v_lshlrev_b32_e32 v248, 16, v42
	v_and_b32_e32 v42, 0xffff0000, v42
	v_lshlrev_b32_e32 v249, 16, v43
	v_and_b32_e32 v43, 0xffff0000, v43
	v_lshlrev_b32_e32 v250, 16, v44
	v_and_b32_e32 v44, 0xffff0000, v44
	v_lshlrev_b32_e32 v251, 16, v45
	v_and_b32_e32 v45, 0xffff0000, v45
	v_lshlrev_b32_e32 v176, 16, v46
	v_and_b32_e32 v46, 0xffff0000, v46
	v_lshlrev_b32_e32 v177, 16, v47
	v_and_b32_e32 v47, 0xffff0000, v47
	v_mul_f32_e32 v178, v246, v246
	v_fmac_f32_e32 v178, v40, v40
	v_fmac_f32_e32 v178, v247, v247
	v_fmac_f32_e32 v178, v41, v41
	v_fmac_f32_e32 v178, v248, v248
	v_fmac_f32_e32 v178, v42, v42
	v_fmac_f32_e32 v178, v249, v249
	v_fmac_f32_e32 v178, v43, v43
	v_fmac_f32_e32 v178, v250, v250
	v_fmac_f32_e32 v178, v44, v44
	v_fmac_f32_e32 v178, v251, v251
	v_fmac_f32_e32 v178, v45, v45
	v_fmac_f32_e32 v178, v176, v176
	v_fmac_f32_e32 v178, v46, v46
	v_fmac_f32_e32 v178, v177, v177
	v_fmac_f32_e32 v178, v47, v47
	s_waitcnt vmcnt(32)
	v_lshlrev_b32_e32 v238, 16, v48
	v_and_b32_e32 v48, 0xffff0000, v48
	v_add_f32_dpp v178, v178, v178 quad_perm:[1,0,3,2] row_mask:0xf bank_mask:0xf bound_ctrl:1
	v_lshlrev_b32_e32 v239, 16, v49
	v_and_b32_e32 v49, 0xffff0000, v49
	v_add_f32_dpp v178, v178, v178 quad_perm:[2,3,0,1] row_mask:0xf bank_mask:0xf bound_ctrl:1
	v_lshlrev_b32_e32 v240, 16, v50
	v_and_b32_e32 v50, 0xffff0000, v50
	v_add_f32_dpp v178, v178, v178 row_half_mirror row_mask:0xf bank_mask:0xf bound_ctrl:1
	v_lshlrev_b32_e32 v241, 16, v51
	v_and_b32_e32 v51, 0xffff0000, v51
	v_add_f32_dpp v178, v178, v178 row_mirror row_mask:0xf bank_mask:0xf bound_ctrl:1
	v_lshlrev_b32_e32 v242, 16, v52
	v_and_b32_e32 v52, 0xffff0000, v52
	v_add_f32_dpp v178, v178, v178 row_bcast:15 row_mask:0xa bank_mask:0xf
	v_lshlrev_b32_e32 v243, 16, v53
	v_and_b32_e32 v53, 0xffff0000, v53
	v_add_f32_dpp v178, v178, v178 row_bcast:31 row_mask:0xc bank_mask:0xf
	v_lshlrev_b32_e32 v244, 16, v54
	v_and_b32_e32 v54, 0xffff0000, v54
	v_lshlrev_b32_e32 v245, 16, v55
	v_and_b32_e32 v55, 0xffff0000, v55
	v_readlane_b32 s0, v178, 63
	s_nop 1
	v_mov_b32_e32 v181, s0
	v_fmamk_f32 v181, v181, 0x3a800000, v161
	v_rsq_f32_e32 v179, v181
	s_nop 0
	v_mul_f32_e32 v246, v246, v179
	v_mul_f32_e32 v40, v40, v179
	v_mul_f32_e32 v247, v247, v179
	v_mul_f32_e32 v41, v41, v179
	v_mul_f32_e32 v248, v248, v179
	v_mul_f32_e32 v42, v42, v179
	v_mul_f32_e32 v249, v249, v179
	v_mul_f32_e32 v43, v43, v179
	v_mul_f32_e32 v250, v250, v179
	v_mul_f32_e32 v44, v44, v179
	v_mul_f32_e32 v251, v251, v179
	v_mul_f32_e32 v45, v45, v179
	v_mul_f32_e32 v176, v176, v179
	v_mul_f32_e32 v46, v46, v179
	v_mul_f32_e32 v177, v177, v179
	v_mul_f32_e32 v47, v47, v179
	v_mul_f32_e32 v246, v246, v56
	v_mul_f32_e32 v40, v40, v57
	v_mul_f32_e32 v247, v247, v58
	v_mul_f32_e32 v41, v41, v59
	v_mul_f32_e32 v248, v248, v60
	v_mul_f32_e32 v42, v42, v61
	v_mul_f32_e32 v249, v249, v62
	v_mul_f32_e32 v43, v43, v63
	v_mul_f32_e32 v250, v250, v64
	v_mul_f32_e32 v44, v44, v65
	v_mul_f32_e32 v251, v251, v66
	v_mul_f32_e32 v45, v45, v67
	v_mul_f32_e32 v176, v176, v68
	v_mul_f32_e32 v46, v46, v69
	v_mul_f32_e32 v177, v177, v70
	v_mul_f32_e32 v47, v47, v71
	v_fmac_f32_e32 v238, v88, v246
	v_fmac_f32_e32 v48, v89, v40
	v_fmac_f32_e32 v239, v90, v247
	v_fmac_f32_e32 v49, v91, v41
	v_fmac_f32_e32 v240, v92, v248
	v_fmac_f32_e32 v50, v93, v42
	v_fmac_f32_e32 v241, v94, v249
	v_fmac_f32_e32 v51, v95, v43
	v_fmac_f32_e32 v242, v96, v250
	v_fmac_f32_e32 v52, v97, v44
	v_fmac_f32_e32 v243, v98, v251
	v_fmac_f32_e32 v53, v99, v45
	v_fmac_f32_e32 v244, v100, v176
	v_fmac_f32_e32 v54, v101, v46
	v_fmac_f32_e32 v245, v102, v177
	v_fmac_f32_e32 v55, v103, v47
	v_cvt_pk_bf16_f32 v120, v238, v48
	v_cvt_pk_bf16_f32 v121, v239, v49
	global_store_dwordx2 v2, v[120:121], s[4:5] offset:0 nt
	v_cvt_pk_bf16_f32 v122, v240, v50
	v_cvt_pk_bf16_f32 v123, v241, v51
	global_store_dwordx2 v2, v[122:123], s[4:5] offset:512 nt
	v_cvt_pk_bf16_f32 v124, v242, v52
	v_cvt_pk_bf16_f32 v125, v243, v53
	global_store_dwordx2 v2, v[124:125], s[4:5] offset:1024 nt
	v_cvt_pk_bf16_f32 v126, v244, v54
	v_cvt_pk_bf16_f32 v127, v245, v55
	global_store_dwordx2 v2, v[126:127], s[4:5] offset:1536 nt
	v_mul_f32_e32 v178, v238, v238
	v_fmac_f32_e32 v178, v48, v48
	v_fmac_f32_e32 v178, v239, v239
	v_fmac_f32_e32 v178, v49, v49
	v_fmac_f32_e32 v178, v240, v240
	v_fmac_f32_e32 v178, v50, v50
	v_fmac_f32_e32 v178, v241, v241
	v_fmac_f32_e32 v178, v51, v51
	v_fmac_f32_e32 v178, v242, v242
	v_fmac_f32_e32 v178, v52, v52
	v_fmac_f32_e32 v178, v243, v243
	v_fmac_f32_e32 v178, v53, v53
	v_fmac_f32_e32 v178, v244, v244
	v_fmac_f32_e32 v178, v54, v54
	v_fmac_f32_e32 v178, v245, v245
	v_fmac_f32_e32 v178, v55, v55
	s_nop 1
	v_add_f32_dpp v178, v178, v178 quad_perm:[1,0,3,2] row_mask:0xf bank_mask:0xf bound_ctrl:1
	s_nop 1
	v_add_f32_dpp v178, v178, v178 quad_perm:[2,3,0,1] row_mask:0xf bank_mask:0xf bound_ctrl:1
	s_nop 1
	v_add_f32_dpp v178, v178, v178 row_half_mirror row_mask:0xf bank_mask:0xf bound_ctrl:1
	s_nop 1
	v_add_f32_dpp v178, v178, v178 row_mirror row_mask:0xf bank_mask:0xf bound_ctrl:1
	s_nop 1
	v_add_f32_dpp v178, v178, v178 row_bcast:15 row_mask:0xa bank_mask:0xf
	s_nop 1
	v_add_f32_dpp v178, v178, v178 row_bcast:31 row_mask:0xc bank_mask:0xf
	s_nop 0
	v_readlane_b32 s0, v178, 63
	s_nop 1
	v_mov_b32_e32 v181, s0
	v_fmamk_f32 v181, v181, 0x3a800000, v161
	v_rsq_f32_e32 v180, v181
	s_nop 0
	v_mul_f32_e32 v238, v238, v180
	v_mul_f32_e32 v48, v48, v180
	v_mul_f32_e32 v239, v239, v180
	v_mul_f32_e32 v49, v49, v180
	v_mul_f32_e32 v240, v240, v180
	v_mul_f32_e32 v50, v50, v180
	v_mul_f32_e32 v241, v241, v180
	v_mul_f32_e32 v51, v51, v180
	v_mul_f32_e32 v242, v242, v180
	v_mul_f32_e32 v52, v52, v180
	v_mul_f32_e32 v243, v243, v180
	v_mul_f32_e32 v53, v53, v180
	v_mul_f32_e32 v244, v244, v180
	v_mul_f32_e32 v54, v54, v180
	v_mul_f32_e32 v245, v245, v180
	v_mul_f32_e32 v55, v55, v180
	v_mul_f32_e32 v238, v238, v72
	v_mul_f32_e32 v48, v48, v73
	v_mul_f32_e32 v239, v239, v74
	v_mul_f32_e32 v49, v49, v75
	v_mul_f32_e32 v240, v240, v76
	v_mul_f32_e32 v50, v50, v77
	v_mul_f32_e32 v241, v241, v78
	v_mul_f32_e32 v51, v51, v79
	v_mul_f32_e32 v242, v242, v80
	v_mul_f32_e32 v52, v52, v81
	v_mul_f32_e32 v243, v243, v82
	v_mul_f32_e32 v53, v53, v83
	v_mul_f32_e32 v244, v244, v84
	v_mul_f32_e32 v54, v54, v85
	v_mul_f32_e32 v245, v245, v86
	v_mul_f32_e32 v55, v55, v87
	v_fma_f32 v238, v238, v104, v134
	v_fma_f32 v48, v48, v105, v135
	v_fma_f32 v239, v239, v106, v136
	v_fma_f32 v49, v49, v107, v137
	v_fma_f32 v240, v240, v108, v138
	v_fma_f32 v50, v50, v109, v139
	v_fma_f32 v241, v241, v110, v140
	v_fma_f32 v51, v51, v111, v141
	v_fma_f32 v242, v242, v112, v142
	v_fma_f32 v52, v52, v113, v143
	v_fma_f32 v243, v243, v114, v144
	v_fma_f32 v53, v53, v115, v145
	v_fma_f32 v244, v244, v116, v146
	v_fma_f32 v54, v54, v117, v147
	v_fma_f32 v245, v245, v118, v148
	v_fma_f32 v55, v55, v119, v149
	v_cvt_pk_bf16_f32 v150, v238, v48
	v_cvt_pk_bf16_f32 v151, v239, v49
	global_store_dwordx2 v2, v[150:151], s[8:9] offset:0
	v_cvt_pk_bf16_f32 v152, v240, v50
	v_cvt_pk_bf16_f32 v153, v241, v51
	global_store_dwordx2 v2, v[152:153], s[8:9] offset:512
	v_cvt_pk_bf16_f32 v154, v242, v52
	v_cvt_pk_bf16_f32 v155, v243, v53
	global_store_dwordx2 v2, v[154:155], s[8:9] offset:1024
	v_cvt_pk_bf16_f32 v156, v244, v54
	v_cvt_pk_bf16_f32 v157, v245, v55
	global_store_dwordx2 v2, v[156:157], s[8:9] offset:1536
	s_waitcnt vmcnt(28)
	v_lshlrev_b32_e32 v246, 16, v8
	v_and_b32_e32 v8, 0xffff0000, v8
	v_lshlrev_b32_e32 v247, 16, v9
	v_and_b32_e32 v9, 0xffff0000, v9
	v_lshlrev_b32_e32 v248, 16, v10
	v_and_b32_e32 v10, 0xffff0000, v10
	v_lshlrev_b32_e32 v249, 16, v11
	v_and_b32_e32 v11, 0xffff0000, v11
	v_lshlrev_b32_e32 v250, 16, v12
	v_and_b32_e32 v12, 0xffff0000, v12
	v_lshlrev_b32_e32 v251, 16, v13
	v_and_b32_e32 v13, 0xffff0000, v13
	v_lshlrev_b32_e32 v176, 16, v14
	v_and_b32_e32 v14, 0xffff0000, v14
	v_lshlrev_b32_e32 v177, 16, v15
	v_and_b32_e32 v15, 0xffff0000, v15
	v_mul_f32_e32 v178, v246, v246
	v_fmac_f32_e32 v178, v8, v8
	v_fmac_f32_e32 v178, v247, v247
	v_fmac_f32_e32 v178, v9, v9
	v_fmac_f32_e32 v178, v248, v248
	v_fmac_f32_e32 v178, v10, v10
	v_fmac_f32_e32 v178, v249, v249
	v_fmac_f32_e32 v178, v11, v11
	v_fmac_f32_e32 v178, v250, v250
	v_fmac_f32_e32 v178, v12, v12
	v_fmac_f32_e32 v178, v251, v251
	v_fmac_f32_e32 v178, v13, v13
	v_fmac_f32_e32 v178, v176, v176
	v_fmac_f32_e32 v178, v14, v14
	v_fmac_f32_e32 v178, v177, v177
	v_fmac_f32_e32 v178, v15, v15
	s_waitcnt vmcnt(24)
	v_lshlrev_b32_e32 v238, 16, v16
	v_and_b32_e32 v16, 0xffff0000, v16
	v_add_f32_dpp v178, v178, v178 quad_perm:[1,0,3,2] row_mask:0xf bank_mask:0xf bound_ctrl:1
	v_lshlrev_b32_e32 v239, 16, v17
	v_and_b32_e32 v17, 0xffff0000, v17
	v_add_f32_dpp v178, v178, v178 quad_perm:[2,3,0,1] row_mask:0xf bank_mask:0xf bound_ctrl:1
	v_lshlrev_b32_e32 v240, 16, v18
	v_and_b32_e32 v18, 0xffff0000, v18
	v_add_f32_dpp v178, v178, v178 row_half_mirror row_mask:0xf bank_mask:0xf bound_ctrl:1
	v_lshlrev_b32_e32 v241, 16, v19
	v_and_b32_e32 v19, 0xffff0000, v19
	v_add_f32_dpp v178, v178, v178 row_mirror row_mask:0xf bank_mask:0xf bound_ctrl:1
	v_lshlrev_b32_e32 v242, 16, v20
	v_and_b32_e32 v20, 0xffff0000, v20
	v_add_f32_dpp v178, v178, v178 row_bcast:15 row_mask:0xa bank_mask:0xf
	v_lshlrev_b32_e32 v243, 16, v21
	v_and_b32_e32 v21, 0xffff0000, v21
	v_add_f32_dpp v178, v178, v178 row_bcast:31 row_mask:0xc bank_mask:0xf
	v_lshlrev_b32_e32 v244, 16, v22
	v_and_b32_e32 v22, 0xffff0000, v22
	v_lshlrev_b32_e32 v245, 16, v23
	v_and_b32_e32 v23, 0xffff0000, v23
	v_readlane_b32 s0, v178, 63
	s_nop 1
	v_mov_b32_e32 v181, s0
	v_fmamk_f32 v181, v181, 0x3a800000, v161
	v_rsq_f32_e32 v179, v181
	s_nop 0
	v_mul_f32_e32 v246, v246, v179
	v_mul_f32_e32 v8, v8, v179
	v_mul_f32_e32 v247, v247, v179
	v_mul_f32_e32 v9, v9, v179
	v_mul_f32_e32 v248, v248, v179
	v_mul_f32_e32 v10, v10, v179
	v_mul_f32_e32 v249, v249, v179
	v_mul_f32_e32 v11, v11, v179
	v_mul_f32_e32 v250, v250, v179
	v_mul_f32_e32 v12, v12, v179
	v_mul_f32_e32 v251, v251, v179
	v_mul_f32_e32 v13, v13, v179
	v_mul_f32_e32 v176, v176, v179
	v_mul_f32_e32 v14, v14, v179
	v_mul_f32_e32 v177, v177, v179
	v_mul_f32_e32 v15, v15, v179
	v_mul_f32_e32 v246, v246, v56
	v_mul_f32_e32 v8, v8, v57
	v_mul_f32_e32 v247, v247, v58
	v_mul_f32_e32 v9, v9, v59
	v_mul_f32_e32 v248, v248, v60
	v_mul_f32_e32 v10, v10, v61
	v_mul_f32_e32 v249, v249, v62
	v_mul_f32_e32 v11, v11, v63
	v_mul_f32_e32 v250, v250, v64
	v_mul_f32_e32 v12, v12, v65
	v_mul_f32_e32 v251, v251, v66
	v_mul_f32_e32 v13, v13, v67
	v_mul_f32_e32 v176, v176, v68
	v_mul_f32_e32 v14, v14, v69
	v_mul_f32_e32 v177, v177, v70
	v_mul_f32_e32 v15, v15, v71
	v_fmac_f32_e32 v238, v88, v246
	v_fmac_f32_e32 v16, v89, v8
	v_fmac_f32_e32 v239, v90, v247
	v_fmac_f32_e32 v17, v91, v9
	v_fmac_f32_e32 v240, v92, v248
	v_fmac_f32_e32 v18, v93, v10
	v_fmac_f32_e32 v241, v94, v249
	v_fmac_f32_e32 v19, v95, v11
	v_fmac_f32_e32 v242, v96, v250
	v_fmac_f32_e32 v20, v97, v12
	v_fmac_f32_e32 v243, v98, v251
	v_fmac_f32_e32 v21, v99, v13
	v_fmac_f32_e32 v244, v100, v176
	v_fmac_f32_e32 v22, v101, v14
	v_fmac_f32_e32 v245, v102, v177
	v_fmac_f32_e32 v23, v103, v15
	v_cvt_pk_bf16_f32 v120, v238, v16
	v_cvt_pk_bf16_f32 v121, v239, v17
	global_store_dwordx2 v3, v[120:121], s[4:5] offset:0 nt
	v_cvt_pk_bf16_f32 v122, v240, v18
	v_cvt_pk_bf16_f32 v123, v241, v19
	global_store_dwordx2 v3, v[122:123], s[4:5] offset:512 nt
	v_cvt_pk_bf16_f32 v124, v242, v20
	v_cvt_pk_bf16_f32 v125, v243, v21
	global_store_dwordx2 v3, v[124:125], s[4:5] offset:1024 nt
	v_cvt_pk_bf16_f32 v126, v244, v22
	v_cvt_pk_bf16_f32 v127, v245, v23
	global_store_dwordx2 v3, v[126:127], s[4:5] offset:1536 nt
	v_mul_f32_e32 v178, v238, v238
	v_fmac_f32_e32 v178, v16, v16
	v_fmac_f32_e32 v178, v239, v239
	v_fmac_f32_e32 v178, v17, v17
	v_fmac_f32_e32 v178, v240, v240
	v_fmac_f32_e32 v178, v18, v18
	v_fmac_f32_e32 v178, v241, v241
	v_fmac_f32_e32 v178, v19, v19
	v_fmac_f32_e32 v178, v242, v242
	v_fmac_f32_e32 v178, v20, v20
	v_fmac_f32_e32 v178, v243, v243
	v_fmac_f32_e32 v178, v21, v21
	v_fmac_f32_e32 v178, v244, v244
	v_fmac_f32_e32 v178, v22, v22
	v_fmac_f32_e32 v178, v245, v245
	v_fmac_f32_e32 v178, v23, v23
	s_nop 1
	v_add_f32_dpp v178, v178, v178 quad_perm:[1,0,3,2] row_mask:0xf bank_mask:0xf bound_ctrl:1
	s_nop 1
	v_add_f32_dpp v178, v178, v178 quad_perm:[2,3,0,1] row_mask:0xf bank_mask:0xf bound_ctrl:1
	s_nop 1
	v_add_f32_dpp v178, v178, v178 row_half_mirror row_mask:0xf bank_mask:0xf bound_ctrl:1
	s_nop 1
	v_add_f32_dpp v178, v178, v178 row_mirror row_mask:0xf bank_mask:0xf bound_ctrl:1
	s_nop 1
	v_add_f32_dpp v178, v178, v178 row_bcast:15 row_mask:0xa bank_mask:0xf
	s_nop 1
	v_add_f32_dpp v178, v178, v178 row_bcast:31 row_mask:0xc bank_mask:0xf
	s_nop 0
	v_readlane_b32 s0, v178, 63
	s_nop 1
	v_mov_b32_e32 v181, s0
	v_fmamk_f32 v181, v181, 0x3a800000, v161
	v_rsq_f32_e32 v180, v181
	s_nop 0
	v_mul_f32_e32 v238, v238, v180
	v_mul_f32_e32 v16, v16, v180
	v_mul_f32_e32 v239, v239, v180
	v_mul_f32_e32 v17, v17, v180
	v_mul_f32_e32 v240, v240, v180
	v_mul_f32_e32 v18, v18, v180
	v_mul_f32_e32 v241, v241, v180
	v_mul_f32_e32 v19, v19, v180
	v_mul_f32_e32 v242, v242, v180
	v_mul_f32_e32 v20, v20, v180
	v_mul_f32_e32 v243, v243, v180
	v_mul_f32_e32 v21, v21, v180
	v_mul_f32_e32 v244, v244, v180
	v_mul_f32_e32 v22, v22, v180
	v_mul_f32_e32 v245, v245, v180
	v_mul_f32_e32 v23, v23, v180
	v_mul_f32_e32 v238, v238, v72
	v_mul_f32_e32 v16, v16, v73
	v_mul_f32_e32 v239, v239, v74
	v_mul_f32_e32 v17, v17, v75
	v_mul_f32_e32 v240, v240, v76
	v_mul_f32_e32 v18, v18, v77
	v_mul_f32_e32 v241, v241, v78
	v_mul_f32_e32 v19, v19, v79
	v_mul_f32_e32 v242, v242, v80
	v_mul_f32_e32 v20, v20, v81
	v_mul_f32_e32 v243, v243, v82
	v_mul_f32_e32 v21, v21, v83
	v_mul_f32_e32 v244, v244, v84
	v_mul_f32_e32 v22, v22, v85
	v_mul_f32_e32 v245, v245, v86
	v_mul_f32_e32 v23, v23, v87
	v_fma_f32 v238, v238, v104, v134
	v_fma_f32 v16, v16, v105, v135
	v_fma_f32 v239, v239, v106, v136
	v_fma_f32 v17, v17, v107, v137
	v_fma_f32 v240, v240, v108, v138
	v_fma_f32 v18, v18, v109, v139
	v_fma_f32 v241, v241, v110, v140
	v_fma_f32 v19, v19, v111, v141
	v_fma_f32 v242, v242, v112, v142
	v_fma_f32 v20, v20, v113, v143
	v_fma_f32 v243, v243, v114, v144
	v_fma_f32 v21, v21, v115, v145
	v_fma_f32 v244, v244, v116, v146
	v_fma_f32 v22, v22, v117, v147
	v_fma_f32 v245, v245, v118, v148
	v_fma_f32 v23, v23, v119, v149
	v_cvt_pk_bf16_f32 v150, v238, v16
	v_cvt_pk_bf16_f32 v151, v239, v17
	global_store_dwordx2 v3, v[150:151], s[8:9] offset:0
	v_cvt_pk_bf16_f32 v152, v240, v18
	v_cvt_pk_bf16_f32 v153, v241, v19
	global_store_dwordx2 v3, v[152:153], s[8:9] offset:512
	v_cvt_pk_bf16_f32 v154, v242, v20
	v_cvt_pk_bf16_f32 v155, v243, v21
	global_store_dwordx2 v3, v[154:155], s[8:9] offset:1024
	v_cvt_pk_bf16_f32 v156, v244, v22
	v_cvt_pk_bf16_f32 v157, v245, v23
	global_store_dwordx2 v3, v[156:157], s[8:9] offset:1536
	s_waitcnt vmcnt(28)
	v_lshlrev_b32_e32 v246, 16, v190
	v_and_b32_e32 v190, 0xffff0000, v190
	v_lshlrev_b32_e32 v247, 16, v191
	v_and_b32_e32 v191, 0xffff0000, v191
	v_lshlrev_b32_e32 v248, 16, v192
	v_and_b32_e32 v192, 0xffff0000, v192
	v_lshlrev_b32_e32 v249, 16, v193
	v_and_b32_e32 v193, 0xffff0000, v193
	v_lshlrev_b32_e32 v250, 16, v194
	v_and_b32_e32 v194, 0xffff0000, v194
	v_lshlrev_b32_e32 v251, 16, v195
	v_and_b32_e32 v195, 0xffff0000, v195
	v_lshlrev_b32_e32 v176, 16, v196
	v_and_b32_e32 v196, 0xffff0000, v196
	v_lshlrev_b32_e32 v177, 16, v197
	v_and_b32_e32 v197, 0xffff0000, v197
	v_mul_f32_e32 v178, v246, v246
	v_fmac_f32_e32 v178, v190, v190
	v_fmac_f32_e32 v178, v247, v247
	v_fmac_f32_e32 v178, v191, v191
	v_fmac_f32_e32 v178, v248, v248
	v_fmac_f32_e32 v178, v192, v192
	v_fmac_f32_e32 v178, v249, v249
	v_fmac_f32_e32 v178, v193, v193
	v_fmac_f32_e32 v178, v250, v250
	v_fmac_f32_e32 v178, v194, v194
	v_fmac_f32_e32 v178, v251, v251
	v_fmac_f32_e32 v178, v195, v195
	v_fmac_f32_e32 v178, v176, v176
	v_fmac_f32_e32 v178, v196, v196
	v_fmac_f32_e32 v178, v177, v177
	v_fmac_f32_e32 v178, v197, v197
	s_waitcnt vmcnt(24)
	v_lshlrev_b32_e32 v238, 16, v198
	v_and_b32_e32 v198, 0xffff0000, v198
	v_add_f32_dpp v178, v178, v178 quad_perm:[1,0,3,2] row_mask:0xf bank_mask:0xf bound_ctrl:1
	v_lshlrev_b32_e32 v239, 16, v199
	v_and_b32_e32 v199, 0xffff0000, v199
	v_add_f32_dpp v178, v178, v178 quad_perm:[2,3,0,1] row_mask:0xf bank_mask:0xf bound_ctrl:1
	v_lshlrev_b32_e32 v240, 16, v200
	v_and_b32_e32 v200, 0xffff0000, v200
	v_add_f32_dpp v178, v178, v178 row_half_mirror row_mask:0xf bank_mask:0xf bound_ctrl:1
	v_lshlrev_b32_e32 v241, 16, v201
	v_and_b32_e32 v201, 0xffff0000, v201
	v_add_f32_dpp v178, v178, v178 row_mirror row_mask:0xf bank_mask:0xf bound_ctrl:1
	v_lshlrev_b32_e32 v242, 16, v202
	v_and_b32_e32 v202, 0xffff0000, v202
	v_add_f32_dpp v178, v178, v178 row_bcast:15 row_mask:0xa bank_mask:0xf
	v_lshlrev_b32_e32 v243, 16, v203
	v_and_b32_e32 v203, 0xffff0000, v203
	v_add_f32_dpp v178, v178, v178 row_bcast:31 row_mask:0xc bank_mask:0xf
	v_lshlrev_b32_e32 v244, 16, v204
	v_and_b32_e32 v204, 0xffff0000, v204
	v_lshlrev_b32_e32 v245, 16, v205
	v_and_b32_e32 v205, 0xffff0000, v205
	v_readlane_b32 s0, v178, 63
	s_nop 1
	v_mov_b32_e32 v181, s0
	v_fmamk_f32 v181, v181, 0x3a800000, v161
	v_rsq_f32_e32 v179, v181
	s_nop 0
	v_mul_f32_e32 v246, v246, v179
	v_mul_f32_e32 v190, v190, v179
	v_mul_f32_e32 v247, v247, v179
	v_mul_f32_e32 v191, v191, v179
	v_mul_f32_e32 v248, v248, v179
	v_mul_f32_e32 v192, v192, v179
	v_mul_f32_e32 v249, v249, v179
	v_mul_f32_e32 v193, v193, v179
	v_mul_f32_e32 v250, v250, v179
	v_mul_f32_e32 v194, v194, v179
	v_mul_f32_e32 v251, v251, v179
	v_mul_f32_e32 v195, v195, v179
	v_mul_f32_e32 v176, v176, v179
	v_mul_f32_e32 v196, v196, v179
	v_mul_f32_e32 v177, v177, v179
	v_mul_f32_e32 v197, v197, v179
	v_mul_f32_e32 v246, v246, v56
	v_mul_f32_e32 v190, v190, v57
	v_mul_f32_e32 v247, v247, v58
	v_mul_f32_e32 v191, v191, v59
	v_mul_f32_e32 v248, v248, v60
	v_mul_f32_e32 v192, v192, v61
	v_mul_f32_e32 v249, v249, v62
	v_mul_f32_e32 v193, v193, v63
	v_mul_f32_e32 v250, v250, v64
	v_mul_f32_e32 v194, v194, v65
	v_mul_f32_e32 v251, v251, v66
	v_mul_f32_e32 v195, v195, v67
	v_mul_f32_e32 v176, v176, v68
	v_mul_f32_e32 v196, v196, v69
	v_mul_f32_e32 v177, v177, v70
	v_mul_f32_e32 v197, v197, v71
	v_fmac_f32_e32 v238, v88, v246
	v_fmac_f32_e32 v198, v89, v190
	v_fmac_f32_e32 v239, v90, v247
	v_fmac_f32_e32 v199, v91, v191
	v_fmac_f32_e32 v240, v92, v248
	v_fmac_f32_e32 v200, v93, v192
	v_fmac_f32_e32 v241, v94, v249
	v_fmac_f32_e32 v201, v95, v193
	v_fmac_f32_e32 v242, v96, v250
	v_fmac_f32_e32 v202, v97, v194
	v_fmac_f32_e32 v243, v98, v251
	v_fmac_f32_e32 v203, v99, v195
	v_fmac_f32_e32 v244, v100, v176
	v_fmac_f32_e32 v204, v101, v196
	v_fmac_f32_e32 v245, v102, v177
	v_fmac_f32_e32 v205, v103, v197
	v_cvt_pk_bf16_f32 v120, v238, v198
	v_cvt_pk_bf16_f32 v121, v239, v199
	global_store_dwordx2 v4, v[120:121], s[4:5] offset:0 nt
	v_cvt_pk_bf16_f32 v122, v240, v200
	v_cvt_pk_bf16_f32 v123, v241, v201
	global_store_dwordx2 v4, v[122:123], s[4:5] offset:512 nt
	v_cvt_pk_bf16_f32 v124, v242, v202
	v_cvt_pk_bf16_f32 v125, v243, v203
	global_store_dwordx2 v4, v[124:125], s[4:5] offset:1024 nt
	v_cvt_pk_bf16_f32 v126, v244, v204
	v_cvt_pk_bf16_f32 v127, v245, v205
	global_store_dwordx2 v4, v[126:127], s[4:5] offset:1536 nt
	v_mul_f32_e32 v178, v238, v238
	v_fmac_f32_e32 v178, v198, v198
	v_fmac_f32_e32 v178, v239, v239
	v_fmac_f32_e32 v178, v199, v199
	v_fmac_f32_e32 v178, v240, v240
	v_fmac_f32_e32 v178, v200, v200
	v_fmac_f32_e32 v178, v241, v241
	v_fmac_f32_e32 v178, v201, v201
	v_fmac_f32_e32 v178, v242, v242
	v_fmac_f32_e32 v178, v202, v202
	v_fmac_f32_e32 v178, v243, v243
	v_fmac_f32_e32 v178, v203, v203
	v_fmac_f32_e32 v178, v244, v244
	v_fmac_f32_e32 v178, v204, v204
	v_fmac_f32_e32 v178, v245, v245
	v_fmac_f32_e32 v178, v205, v205
	s_nop 1
	v_add_f32_dpp v178, v178, v178 quad_perm:[1,0,3,2] row_mask:0xf bank_mask:0xf bound_ctrl:1
	s_nop 1
	v_add_f32_dpp v178, v178, v178 quad_perm:[2,3,0,1] row_mask:0xf bank_mask:0xf bound_ctrl:1
	s_nop 1
	v_add_f32_dpp v178, v178, v178 row_half_mirror row_mask:0xf bank_mask:0xf bound_ctrl:1
	s_nop 1
	v_add_f32_dpp v178, v178, v178 row_mirror row_mask:0xf bank_mask:0xf bound_ctrl:1
	s_nop 1
	v_add_f32_dpp v178, v178, v178 row_bcast:15 row_mask:0xa bank_mask:0xf
	s_nop 1
	v_add_f32_dpp v178, v178, v178 row_bcast:31 row_mask:0xc bank_mask:0xf
	s_nop 0
	v_readlane_b32 s0, v178, 63
	s_nop 1
	v_mov_b32_e32 v181, s0
	v_fmamk_f32 v181, v181, 0x3a800000, v161
	v_rsq_f32_e32 v180, v181
	s_nop 0
	v_mul_f32_e32 v238, v238, v180
	v_mul_f32_e32 v198, v198, v180
	v_mul_f32_e32 v239, v239, v180
	v_mul_f32_e32 v199, v199, v180
	v_mul_f32_e32 v240, v240, v180
	v_mul_f32_e32 v200, v200, v180
	v_mul_f32_e32 v241, v241, v180
	v_mul_f32_e32 v201, v201, v180
	v_mul_f32_e32 v242, v242, v180
	v_mul_f32_e32 v202, v202, v180
	v_mul_f32_e32 v243, v243, v180
	v_mul_f32_e32 v203, v203, v180
	v_mul_f32_e32 v244, v244, v180
	v_mul_f32_e32 v204, v204, v180
	v_mul_f32_e32 v245, v245, v180
	v_mul_f32_e32 v205, v205, v180
	v_mul_f32_e32 v238, v238, v72
	v_mul_f32_e32 v198, v198, v73
	v_mul_f32_e32 v239, v239, v74
	v_mul_f32_e32 v199, v199, v75
	v_mul_f32_e32 v240, v240, v76
	v_mul_f32_e32 v200, v200, v77
	v_mul_f32_e32 v241, v241, v78
	v_mul_f32_e32 v201, v201, v79
	v_mul_f32_e32 v242, v242, v80
	v_mul_f32_e32 v202, v202, v81
	v_mul_f32_e32 v243, v243, v82
	v_mul_f32_e32 v203, v203, v83
	v_mul_f32_e32 v244, v244, v84
	v_mul_f32_e32 v204, v204, v85
	v_mul_f32_e32 v245, v245, v86
	v_mul_f32_e32 v205, v205, v87
	v_fma_f32 v238, v238, v104, v134
	v_fma_f32 v198, v198, v105, v135
	v_fma_f32 v239, v239, v106, v136
	v_fma_f32 v199, v199, v107, v137
	v_fma_f32 v240, v240, v108, v138
	v_fma_f32 v200, v200, v109, v139
	v_fma_f32 v241, v241, v110, v140
	v_fma_f32 v201, v201, v111, v141
	v_fma_f32 v242, v242, v112, v142
	v_fma_f32 v202, v202, v113, v143
	v_fma_f32 v243, v243, v114, v144
	v_fma_f32 v203, v203, v115, v145
	v_fma_f32 v244, v244, v116, v146
	v_fma_f32 v204, v204, v117, v147
	v_fma_f32 v245, v245, v118, v148
	v_fma_f32 v205, v205, v119, v149
	v_cvt_pk_bf16_f32 v150, v238, v198
	v_cvt_pk_bf16_f32 v151, v239, v199
	global_store_dwordx2 v4, v[150:151], s[8:9] offset:0
	v_cvt_pk_bf16_f32 v152, v240, v200
	v_cvt_pk_bf16_f32 v153, v241, v201
	global_store_dwordx2 v4, v[152:153], s[8:9] offset:512
	v_cvt_pk_bf16_f32 v154, v242, v202
	v_cvt_pk_bf16_f32 v155, v243, v203
	global_store_dwordx2 v4, v[154:155], s[8:9] offset:1024
	v_cvt_pk_bf16_f32 v156, v244, v204
	v_cvt_pk_bf16_f32 v157, v245, v205
	global_store_dwordx2 v4, v[156:157], s[8:9] offset:1536
	s_mov_b64 s[0:1], 0
	s_branch .LBB0_190
